# hand-written K head-norm phase (8 lanes/item, 16B accesses, DPP); attention items batch-per-XCD; 8 XCD-local seams (guarded)
# speedup vs baseline: 1.0395x; 1.0092x over previous
; DI unsigned xb_ld(unsigned* p) { return __hip_atomic_load(p, __ATOMIC_RELAXED, __HIP_MEMORY_SCOPE_AGENT); }
; DI unsigned xb_add(unsigned* p, unsigned v) { return __hip_atomic_fetch_add(p, v, __ATOMIC_RELAXED, __HIP_MEMORY_SCOPE_AGENT); }
; #define XB_SPIN(cond, bar) do { unsigned _sp = 0; while (cond) { __builtin_amdgcn_s_sleep(1); \
;     if ((++_sp & 255u) == 0u) { if (xb_ld(&(bar)[XB_TMO])) break; if (_sp > XB_SPIN_CAP) { atomicAdd(&(bar)[XB_TMO], 1u); break; } } } } while (0)
; DI void xcd_barrier(const XcdBarrier& b) {
;     ...
;     const unsigned old = xb_add(&bar[XB_XSUB(b.x)], 1u);
;     const unsigned gen = old / nloc;
;     if (old + 1u == (gen + 1u) * nloc) {
;       __builtin_amdgcn_fence(__ATOMIC_RELEASE, "agent");
;       asm volatile("s_waitcnt vmcnt(0)" ::: "memory");
;       const unsigned og = xb_add(&bar[XB_TOP], 1u);
;       const unsigned tg = og / nx;
;       if (og + 1u == (tg + 1u) * nx) xb_add(&bar[XB_TOPGEN], 1u);
;       else XB_SPIN(xb_ld(&bar[XB_TOPGEN]) == tg, bar);
;       __builtin_amdgcn_fence(__ATOMIC_ACQUIRE, "agent");
;       xb_add(&bar[XB_XGEN(b.x)], 1u);
.LBB0_409:
	s_andn2_saveexec_b64 s[6:7], s[6:7]
	s_cbranch_execz .LBB0_429
	s_mov_b64 s[6:7], exec
	v_mov_b32_e32 v255, 0
	ds_read_b32 v255, v255 offset:264
	s_waitcnt lgkmcnt(0)
	v_cmp_ne_u32_e32 vcc, 0, v255
	s_cbranch_vccnz .LBB0_426
	buffer_wbl2 sc1
	s_waitcnt lgkmcnt(0)
	s_waitcnt vmcnt(0)
	v_mbcnt_lo_u32_b32 v1, s6, 0
	v_mbcnt_hi_u32_b32 v1, s7, v1
	v_cmp_eq_u32_e32 vcc, 0, v1
	s_and_saveexec_b64 s[8:9], vcc
	s_cbranch_execz .LBB0_412
	s_bcnt1_i32_b64 s6, s[6:7]
	v_mov_b32_e32 v3, 0xbfa3000
	v_mov_b32_e32 v4, s6
	global_atomic_add v3, v3, v4, s[86:87] offset:1024 sc0

; template <int LAYER>
; DI void attn_phase(const Params& p, char* smem) {
;     ...
;   const int xcd = (int)(blockIdx.x & 7), lb = (int)(blockIdx.x >> 3), L = (int)(gridDim.x >> 3);
;   for (int j = lb; j < 192 + 64; j += L) {
;     if (j < 192) {
;       const int hl = j >> 4, qi = j & 15, qt = ((j / L) & 1) ? (15 - qi) : qi, bh = hl * 8 + xcd, b = bh / 12, hd = bh % 12, q0 = qt * 256;
;       const size_t tok0 = (size_t)b * SEQ;
;       bf16_t* O = mix + (tok0 + q0) * DM + hd * 64;
;       if (LAYER == 0) {
;         const bf16_t* P = (const bf16_t*)(ws + O_P);
;         attn_item<64, 2, false, false>(P + (tok0 + q0) * 2560 + hd * 64, 2560, P + tok0 * 2560 + 768 + hd * 64, 2560, P + tok0 * 2560 + 1536 + hd * 64, 2560,
;                                        q0, q0 / 64 + 4, O, 0.125f, smem, nullptr, 1.f, nullptr, nullptr);
.LBB0_459:
	s_and_b64 vcc, exec, s[0:1]
	s_cbranch_vccz .LBB0_432
	v_readlane_b32 s0, v254, 22
	s_mul_hi_u32 s0, s53, s0
	s_mul_i32 s1, s0, s42
	s_sub_i32 s1, s53, s1
	s_add_i32 s3, s0, 1
	s_sub_i32 s6, s1, s42
	s_cmp_ge_u32 s1, s42
	s_cselect_b32 s0, s3, s0
	s_cselect_b32 s1, s6, s1
	s_add_i32 s3, s0, 1
	s_cmp_ge_u32 s1, s42
	s_cselect_b32 s0, s3, s0
	s_lshr_b32 s1, s53, 1
	s_and_b32 s1, s1, 0x78
	s_or_b32 s1, s1, s52
	s_mov_b32 s3, s52
	s_lshr_b32 s1, s53, 4
	s_lshl_b32 s6, s53, 8
	s_and_b32 s6, s6, 0xf00
	s_and_b32 s0, s0, 1
	s_xor_b32 s7, s6, 0xf00
	s_cmp_eq_u32 s0, 0
	s_cselect_b32 s10, s6, s7
	s_lshl_b32 s0, s3, 12
	s_or_b32 s70, s10, s0
	s_lshl_b32 s55, s1, 6
	s_mul_i32 s6, s70, 0x1400
	s_mul_hi_u32 s0, s70, 0x1400
	s_add_u32 s6, s46, s6
	s_addc_u32 s0, s47, s0
	s_lshl_b32 s8, s1, 7
	s_add_u32 s6, s6, s8
	s_addc_u32 s7, s0, 0
	s_mul_i32 s0, s3, 0xa00000
	s_mov_b32 s1, s71
	s_lshl_b64 s[0:1], s[0:1], 1
	s_add_u32 s0, s46, s0
	s_addc_u32 s1, s47, s1
	s_add_u32 s0, s0, s8
	v_mov_b32_e32 v26, v212
	s_addc_u32 s1, s1, 0
	s_lshr_b32 s64, s10, 6
	s_add_i32 s64, s64, 4
	v_ashrrev_i32_e32 v0, 31, v26
	v_lshrrev_b32_e32 v0, 29, v0
	s_lshl_b32 s3, s64, 6
	v_add_u32_e32 v0, v26, v0
	s_add_i32 s11, s3, 0xffffff80
	v_ashrrev_i32_e32 v140, 3, v0
	v_add_u32_e32 v0, s11, v140
	v_mov_b64_e32 v[18:19], s[0:1]
	v_mad_i64_i32 v[2:3], s[8:9], v0, s93, v[18:19]
	v_lshlrev_b32_e32 v0, 6, v140
	v_lshlrev_b32_e32 v28, 3, v26
	v_add_u32_e32 v29, 0x200, v26
	v_sub_u32_e32 v4, v28, v0
	v_ashrrev_i32_e32 v0, 31, v29
	v_lshrrev_b32_e32 v0, 29, v0
	v_add_u32_e32 v0, v29, v0
	v_ashrrev_i32_e32 v5, 31, v4
	v_ashrrev_i32_e32 v141, 3, v0
	v_lshlrev_b32_e32 v27, 4, v26
	v_lshlrev_b64 v[20:21], 1, v[4:5]
	v_add_u32_e32 v0, s11, v141
	v_lshl_add_u64 v[2:3], v[2:3], 0, v[20:21]
	s_waitcnt vmcnt(10)
	v_mad_i64_i32 v[6:7], s[8:9], v0, s93, v[18:19]
	v_lshlrev_b32_e32 v0, 6, v141
	v_lshlrev_b32_e32 v8, 3, v29
	s_waitcnt vmcnt(9)
	v_and_b32_e32 v10, 0x70, v27
	v_mov_b32_e32 v11, v1
	v_ashrrev_i32_e32 v142, 3, v26
	global_load_dwordx4 v[2:5], v[2:3], off offset:1536
	v_sub_u32_e32 v8, v8, v0
	v_lshl_add_u64 v[116:117], s[0:1], 0, v[10:11]
	v_add_u32_e32 v0, s11, v142
	v_ashrrev_i32_e32 v143, 3, v29
	v_ashrrev_i32_e32 v31, 1, v26
	v_ashrrev_i32_e32 v9, 31, v8
	v_mad_i64_i32 v[10:11], s[8:9], v0, s93, v[116:117]
	v_add_u32_e32 v0, s11, v143
	v_bfe_u32 v30, v26, 5, 1
	v_bfi_b32 v118, s12, v31, v26
	v_mov_b64_e32 v[24:25], s[6:7]
	v_lshlrev_b64 v[22:23], 1, v[8:9]
	v_mad_i64_i32 v[14:15], s[8:9], v0, s93, v[116:117]
	v_mad_i64_i32 v[24:25], s[6:7], v118, s93, v[24:25]
	v_lshlrev_b32_e32 v0, 4, v30
	v_lshl_add_u64 v[6:7], v[6:7], 0, v[22:23]
	v_lshl_add_u64 v[24:25], v[24:25], 0, v[0:1]
	s_addk_i32 s3, 0xff00
	global_load_dwordx4 v[6:9], v[6:7], off offset:1536
	s_nop 0
	global_load_dwordx4 v[10:13], v[10:11], off offset:3072
	s_nop 0
	global_load_dwordx4 v[14:17], v[14:15], off offset:3072
	s_nop 0
	global_load_dwordx4 v[80:83], v[24:25], off
	global_load_dwordx4 v[84:87], v[24:25], off offset:32
	global_load_dwordx4 v[88:91], v[24:25], off offset:64
	global_load_dwordx4 v[92:95], v[24:25], off offset:96
	v_add_u32_e32 v24, s3, v140
	v_add_u32_e32 v32, s3, v141
	v_mad_i64_i32 v[24:25], s[6:7], v24, s93, v[18:19]
	v_mad_i64_i32 v[18:19], s[6:7], v32, s93, v[18:19]
	v_lshl_add_u64 v[24:25], v[24:25], 0, v[20:21]
	v_lshl_add_u64 v[18:19], v[18:19], 0, v[22:23]
	global_load_dwordx4 v[96:99], v[24:25], off offset:1536
	global_load_dwordx4 v[100:103], v[18:19], off offset:1536
	v_add_u32_e32 v18, s3, v142
	v_mad_i64_i32 v[18:19], s[6:7], v18, s93, v[116:117]
	v_add_u32_e32 v24, s3, v143
	v_mad_i64_i32 v[24:25], s[6:7], v24, s93, v[116:117]
	global_load_dwordx4 v[104:107], v[18:19], off offset:3072
	global_load_dwordx4 v[108:111], v[24:25], off offset:3072
	v_and_b32_e32 v19, 0xffffffe0, v31
	v_mul_lo_u32 v31, v140, s77
	v_lshlrev_b32_e32 v32, 7, v140
	v_add_u32_e32 v31, 0x110, v31
	v_sub_u32_e32 v32, v27, v32
	v_add_u32_e32 v147, v31, v32
	v_and_b32_e32 v24, 16, v26
	v_lshlrev_b32_e32 v25, 2, v26
	v_and_or_b32 v24, v25, 12, v24
	v_and_b32_e32 v18, 31, v26
	v_add_u32_e32 v144, s10, v19
	v_and_b32_e32 v19, 0xc0, v27
	v_lshlrev_b32_e32 v24, 1, v24
	v_lshlrev_b32_e32 v25, 8, v30
	v_or_b32_e32 v145, v144, v18
	s_lshr_b32 s3, s64, 1
	v_lshlrev_b32_e32 v149, 2, v30
	v_cmp_eq_u32_e64 s[6:7], 0, v30
	v_lshl_add_u64 v[120:121], s[0:1], 0, v[20:21]
	v_lshl_add_u64 v[122:123], s[0:1], 0, v[22:23]
	s_mov_b32 s69, 0
	v_ashrrev_i32_e32 v119, 31, v118
	s_mov_b32 s74, 2
	s_add_i32 s68, s3, -1
	v_or_b32_e32 v146, 31, v144
	s_or_b32 s92, s10, 0xff
	v_mov_b32_e32 v125, 1.0
	s_waitcnt vmcnt(11)
	ds_write_b128 v147, v[2:5]
	v_mul_lo_u32 v2, v141, s77
	v_lshlrev_b32_e32 v3, 7, v141
	v_lshlrev_b32_e32 v4, 4, v29
	v_add_u32_e32 v2, 0x110, v2
	v_sub_u32_e32 v3, v4, v3
	v_add_u32_e32 v148, v2, v3
	v_lshlrev_b32_e32 v2, 11, v26
	v_and_b32_e32 v2, 0x2000, v2
	v_and_b32_e32 v3, 48, v27
	v_add3_u32 v2, s13, v2, v3
	v_and_b32_e32 v3, 0xffffffc0, v28
	v_add_u32_e32 v150, v2, v3
	v_or3_b32 v2, v25, v19, v24
	v_mul_u32_u24_e32 v3, 0x90, v18
	v_add3_u32 v151, s13, v0, v3
	v_add_u32_e32 v152, 0x110, v2
	v_mov_b32_e32 v0, v1
	v_mov_b32_e32 v2, v1
	v_mov_b32_e32 v3, v1
	v_mov_b32_e32 v4, v1
	v_mov_b32_e32 v5, v1
	s_waitcnt vmcnt(10)
	ds_write_b128 v148, v[6:9]
	s_waitcnt vmcnt(9)
	ds_write_b128 v150, v[10:13] offset:18432
	s_waitcnt vmcnt(8)
	ds_write_b128 v150, v[14:17] offset:22528
	v_mov_b32_e32 v14, v1
	v_mov_b32_e32 v15, v1
	v_mov_b32_e32 v6, v1
	v_mov_b32_e32 v7, v1
	v_mov_b32_e32 v8, v1
	v_mov_b32_e32 v9, v1
	v_mov_b32_e32 v10, v1
	v_mov_b32_e32 v11, v1
	v_mov_b32_e32 v12, v1
	v_mov_b32_e32 v13, v1
	v_mov_b64_e32 v[30:31], v[14:15]
	v_mov_b64_e32 v[46:47], v[14:15]
	v_mov_b64_e32 v[28:29], v[12:13]
	v_mov_b64_e32 v[26:27], v[10:11]
	v_mov_b64_e32 v[24:25], v[8:9]
	v_mov_b64_e32 v[22:23], v[6:7]
	v_mov_b64_e32 v[20:21], v[4:5]
	v_mov_b64_e32 v[18:19], v[2:3]
	v_mov_b64_e32 v[16:17], v[0:1]
	v_mov_b64_e32 v[44:45], v[12:13]
	v_mov_b64_e32 v[42:43], v[10:11]
	v_mov_b64_e32 v[40:41], v[8:9]
	v_mov_b64_e32 v[38:39], v[6:7]
	v_mov_b64_e32 v[36:37], v[4:5]
	v_mov_b64_e32 v[34:35], v[2:3]
	v_mov_b64_e32 v[32:33], v[0:1]
	s_waitcnt lgkmcnt(0)
	s_barrier
	s_branch .LBB0_464

; DI unsigned xb_ld(unsigned* p) { return __hip_atomic_load(p, __ATOMIC_RELAXED, __HIP_MEMORY_SCOPE_AGENT); }
; DI unsigned xb_add(unsigned* p, unsigned v) { return __hip_atomic_fetch_add(p, v, __ATOMIC_RELAXED, __HIP_MEMORY_SCOPE_AGENT); }
; #define XB_SPIN(cond, bar) do { unsigned _sp = 0; while (cond) { __builtin_amdgcn_s_sleep(1); \
;     if ((++_sp & 255u) == 0u) { if (xb_ld(&(bar)[XB_TMO])) break; if (_sp > XB_SPIN_CAP) { atomicAdd(&(bar)[XB_TMO], 1u); break; } } } } while (0)
; DI void xcd_barrier(const XcdBarrier& b) {
;     ...
;     if (old + 1u == (gen + 1u) * nloc) {
;       __builtin_amdgcn_fence(__ATOMIC_RELEASE, "agent");
;       asm volatile("s_waitcnt vmcnt(0)" ::: "memory");
;       const unsigned og = xb_add(&bar[XB_TOP], 1u);
;       const unsigned tg = og / nx;
;       if (og + 1u == (tg + 1u) * nx) xb_add(&bar[XB_TOPGEN], 1u);
;       else XB_SPIN(xb_ld(&bar[XB_TOPGEN]) == tg, bar);
.LBB0_1089:
	s_andn2_saveexec_b64 s[2:3], s[8:9]
	s_cbranch_execz .LBB0_1109
	s_mov_b64 s[8:9], exec
	v_mov_b32_e32 v255, 0
	ds_read_b32 v255, v255 offset:264
	s_waitcnt lgkmcnt(0)
	v_cmp_ne_u32_e32 vcc, 0, v255
	s_cbranch_vccnz .LBB0_1106
	buffer_wbl2 sc1
	s_waitcnt lgkmcnt(0)
	s_waitcnt vmcnt(0)
	v_mbcnt_lo_u32_b32 v0, s8, 0
	v_mbcnt_hi_u32_b32 v0, s9, v0
	v_cmp_eq_u32_e32 vcc, 0, v0
	s_and_saveexec_b64 s[10:11], vcc
	s_cbranch_execz .LBB0_1092
	s_bcnt1_i32_b64 s2, s[8:9]
	v_mov_b32_e32 v2, 0xbfa3000
	v_mov_b32_e32 v3, s2
	global_atomic_add v2, v2, v3, s[86:87] offset:1024 sc0
.LBB0_1092:
	s_or_b64 exec, exec, s[10:11]
	v_cvt_f32_u32_e32 v3, v1
	s_waitcnt vmcnt(0)
	v_readfirstlane_b32 s2, v2
	s_add_u32 s10, s86, 0xbfa3500
	s_addc_u32 s11, s87, 0
	v_rcp_iflag_f32_e32 v3, v3
	v_add_u32_e32 v0, s2, v0
	v_add_u32_e32 v4, 1, v0
	s_mov_b64 s[12:13], -1
	v_mul_f32_e32 v2, 0x4f7ffffe, v3
	v_cvt_u32_f32_e32 v2, v2
	v_sub_u32_e32 v3, 0, v1
	v_mul_lo_u32 v3, v3, v2
	v_mul_hi_u32 v3, v2, v3
	v_add_u32_e32 v2, v2, v3
	v_mul_hi_u32 v2, v0, v2
	v_mul_lo_u32 v3, v2, v1
	v_sub_u32_e32 v0, v0, v3
	v_add_u32_e32 v5, 1, v2
	v_cmp_ge_u32_e32 vcc, v0, v1
	v_sub_u32_e32 v3, v0, v1
	s_nop 0
	v_cndmask_b32_e32 v2, v2, v5, vcc
	v_cndmask_b32_e32 v0, v0, v3, vcc
	v_add_u32_e32 v3, 1, v2
	v_cmp_ge_u32_e32 vcc, v0, v1
	s_nop 1
	v_cndmask_b32_e32 v2, v2, v3, vcc
	v_mul_lo_u32 v0, v1, v2
	v_add_u32_e32 v0, v0, v1
	v_cmp_ne_u32_e32 vcc, v4, v0
	v_mov_b64_e32 v[0:1], s[10:11]
	s_and_saveexec_b64 s[8:9], vcc
	s_cbranch_execz .LBB0_1104
	v_mov_b32_e32 v0, 0
	global_load_dword v1, v0, s[10:11] sc1
	s_mov_b64 s[26:27], 0
	s_waitcnt vmcnt(0)
	v_cmp_eq_u32_e32 vcc, v1, v2
	s_and_saveexec_b64 s[24:25], vcc
	s_cbranch_execz .LBB0_1103
	s_add_u32 s12, s86, 0xbfa0200
	s_addc_u32 s13, s87, 0
	s_mov_b32 s2, 1
	s_branch .LBB0_1096

; DI int launder_tid() { int t = threadIdx.x; asm volatile("" : "+v"(t)); return t; }
; template <int D, bool ROPE>
; DI void headnorm_phase(const bf16_t* src1, int ld1, int hs1, const bf16_t* src2, int ld2, int hs2, bf16_t* dst, int ldd, int hsd,
;                        const float* __restrict__ gain, int nrows, int nheads, const int* __restrict__ pos, float oscale) {
;   constexpr int NM = D / 16, U = 8;
;   const int tidh = launder_tid();
;   const int s = tidh & 15;
;   const long nitems = (long)nrows * nheads;
;   const long stride = (long)gridDim.x * (NTHREADS / 16);
;   float gn[NM];
; #pragma unroll
;   for (int m = 0; m < NM; ++m) gn[m] = gain[s + 16 * m] * oscale;
;   const float invf = ROPE ? exp2f(-(float)s * (13.287712379549449f / 16.f)) : 0.f;
;   for (long it0 = (long)blockIdx.x * (NTHREADS / 16) + (tidh >> 4); it0 < nitems; it0 += stride * U) {
;     float v[U][NM];
;     int rowv[U], hdv[U];
; #pragma unroll
;     for (int u = 0; u < U; ++u) {
;       long it = it0 + stride * u; if (it >= nitems) it = it0;
;       const int row = (int)(it / nheads), hd = (int)(it - (long)row * nheads);
;       rowv[u] = row; hdv[u] = hd;
; #pragma unroll
;       for (int m = 0; m < NM; ++m)
;         v[u][m] = (m < 4) ? bf2f(src1[(size_t)row * ld1 + hd * hs1 + s + 16 * m]) : bf2f(src2[(size_t)row * ld2 + hd * hs2 + s + 16 * (m - 4)]);
;     }
; #pragma unroll
;     for (int u = 0; u < U; ++u) {
;       float ss = 0.f;
; #pragma unroll
;       for (int m = 0; m < NM; ++m) ss += v[u][m] * v[u][m];
;       ss += __shfl_xor(ss, 1); ss += __shfl_xor(ss, 2); ss += __shfl_xor(ss, 4); ss += __shfl_xor(ss, 8);
;       const float rstd = rsqrtf(ss * (1.f / D) + EPS);
; #pragma unroll
;       for (int m = 0; m < NM; ++m) v[u][m] = v[u][m] * rstd * gn[m];
;       if (ROPE) {
;         const float ang = (float)pos[rowv[u]] * invf;
;         float rev = ang * 0.15915494309189535f;
;         rev = rev - floorf(rev);
;         const float sn = __builtin_amdgcn_sinf(rev), cs = __builtin_amdgcn_cosf(rev);
;         const float x1 = v[u][NM - 2], x2 = v[u][NM - 1];
;         v[u][NM - 2] = x1 * cs - x2 * sn;
;         v[u][NM - 1] = x2 * cs + x1 * sn;
;       }
;     }
; #pragma unroll
;     for (int u = 0; u < U; ++u)
; #pragma unroll
;       for (int m = 0; m < NM; ++m) dst[(size_t)rowv[u] * ldd + hdv[u] * hsd + s + 16 * m] = tobf(v[u][m]);
.LBB0_1109:
	s_or_b64 exec, exec, s[0:1]
	v_readlane_b32 s12, v254, 20
	v_mov_b32_e32 v0, v212
	v_readlane_b32 s13, v254, 21
	s_waitcnt lgkmcnt(0)
	s_barrier
	s_mov_b64 s[6:7], exec
	v_and_b32_e32 v1, 63, v0
	v_lshrrev_b32_e32 v2, 6, v0
	v_and_b32_e32 v3, 7, v1
	v_lshrrev_b32_e32 v4, 3, v1
	v_lshlrev_b32_e32 v5, 5, v3
	v_readfirstlane_b32 s0, v2
	global_load_dwordx4 v[8:11], v5, s[82:83]
	global_load_dwordx4 v[12:15], v5, s[82:83] offset:16
	v_lshlrev_b32_e32 v6, 3, v3
	global_load_dwordx2 v[16:17], v6, s[82:83] offset:256
	global_load_dwordx2 v[18:19], v6, s[82:83] offset:320
	v_lshlrev_b32_e32 v7, 1, v3
	v_cvt_f32_u32_e32 v20, v7
	v_add_f32_e32 v21, 1.0, v20
	v_mul_f32_e32 v20, 0xbf549a78, v20
	v_mul_f32_e32 v21, 0xbf549a78, v21
	v_exp_f32_e32 v20, v20
	v_exp_f32_e32 v21, v21
	v_lshlrev_b32_e32 v22, 4, v3
	v_lshlrev_b32_e32 v23, 2, v3
	v_mov_b32_e32 v24, 0x358637bd
	s_and_b32 s13, s12, 7
	s_mul_i32 s13, s13, 0xc000
	v_add_u32_e32 v4, s13, v4
	s_lshr_b32 s1, s12, 3
	s_lshl_b32 s1, s1, 3
	s_add_i32 s1, s1, s0
	s_lshl_b32 s1, s1, 5
	s_lshl_b32 s2, s88, 5
	s_mov_b32 s3, 0x3c2aaaab
	s_mov_b32 s18, 0xaaaaaaab
	s_movk_i32 s19, 0xc0
	s_add_u32 s8, s86, 0x15fa4000
	s_addc_u32 s9, s87, 0
	s_add_u32 s10, s86, 0xbfa4800
	s_addc_u32 s11, s87, 0
	s_waitcnt vmcnt(0)
.Lhp_loop:
	s_cmp_lt_u32 s1, 0xc000
	s_cbranch_scc0 .Lhp_done
	v_add_u32_e32 v90, s1, v4
	v_mul_hi_u32 v91, v90, s18
	v_lshrrev_b32_e32 v91, 3, v91
	v_mul_u32_u24_e32 v92, 12, v91
	v_sub_u32_e32 v92, v90, v92
	v_mul_u32_u24_e32 v93, 0x900, v91
	v_mad_u32_u24 v93, v92, s19, v93
	v_add_u32_e32 v32, v93, v22
	v_add_u32_e32 v33, v93, v23
	v_mul_u32_u24_e32 v94, 0xb00, v91
	v_add_u32_e32 v94, v94, v23
	v_lshlrev_b32_e32 v95, 2, v91
	global_load_dwordx4 v[36:39], v32, s[8:9]
	global_load_dword v40, v94, s[10:11]
	global_load_dword v41, v94, s[10:11] offset:32
	global_load_dword v42, v95, s[48:49]
	v_add3_u32 v90, s1, v4, 8
	v_mul_hi_u32 v91, v90, s18
	v_lshrrev_b32_e32 v91, 3, v91
	v_mul_u32_u24_e32 v92, 12, v91
	v_sub_u32_e32 v92, v90, v92
	v_mul_u32_u24_e32 v93, 0x900, v91
	v_mad_u32_u24 v93, v92, s19, v93
	v_add_u32_e32 v44, v93, v22
	v_add_u32_e32 v45, v93, v23
	v_mul_u32_u24_e32 v94, 0xb00, v91
	v_add_u32_e32 v94, v94, v23
	v_lshlrev_b32_e32 v95, 2, v91
	global_load_dwordx4 v[48:51], v44, s[8:9]
	global_load_dword v52, v94, s[10:11]
	global_load_dword v53, v94, s[10:11] offset:32
	global_load_dword v54, v95, s[48:49]
	v_add3_u32 v90, s1, v4, 16
	v_mul_hi_u32 v91, v90, s18
	v_lshrrev_b32_e32 v91, 3, v91
	v_mul_u32_u24_e32 v92, 12, v91
	v_sub_u32_e32 v92, v90, v92
	v_mul_u32_u24_e32 v93, 0x900, v91
	v_mad_u32_u24 v93, v92, s19, v93
	v_add_u32_e32 v56, v93, v22
	v_add_u32_e32 v57, v93, v23
	v_mul_u32_u24_e32 v94, 0xb00, v91
	v_add_u32_e32 v94, v94, v23
	v_lshlrev_b32_e32 v95, 2, v91
	global_load_dwordx4 v[60:63], v56, s[8:9]
	global_load_dword v64, v94, s[10:11]
	global_load_dword v65, v94, s[10:11] offset:32
	global_load_dword v66, v95, s[48:49]
	v_add3_u32 v90, s1, v4, 24
	v_mul_hi_u32 v91, v90, s18
	v_lshrrev_b32_e32 v91, 3, v91
	v_mul_u32_u24_e32 v92, 12, v91
	v_sub_u32_e32 v92, v90, v92
	v_mul_u32_u24_e32 v93, 0x900, v91
	v_mad_u32_u24 v93, v92, s19, v93
	v_add_u32_e32 v68, v93, v22
	v_add_u32_e32 v69, v93, v23
	v_mul_u32_u24_e32 v94, 0xb00, v91
	v_add_u32_e32 v94, v94, v23
	v_lshlrev_b32_e32 v95, 2, v91
	global_load_dwordx4 v[72:75], v68, s[8:9]
	global_load_dword v76, v94, s[10:11]
	global_load_dword v77, v94, s[10:11] offset:32
	global_load_dword v78, v95, s[48:49]
	s_waitcnt vmcnt(12)
	v_lshlrev_b32_e32 v100, 16, v36
	v_and_b32_e32 v101, 0xffff0000, v36
	v_lshlrev_b32_e32 v102, 16, v37
	v_and_b32_e32 v103, 0xffff0000, v37
	v_lshlrev_b32_e32 v104, 16, v38
	v_and_b32_e32 v105, 0xffff0000, v38
	v_lshlrev_b32_e32 v106, 16, v39
	v_and_b32_e32 v107, 0xffff0000, v39
	v_lshlrev_b32_e32 v108, 16, v40
	v_and_b32_e32 v109, 0xffff0000, v40
	v_lshlrev_b32_e32 v110, 16, v41
	v_and_b32_e32 v111, 0xffff0000, v41
	v_mul_f32_e32 v112, v100, v100
	v_fmac_f32_e32 v112, v101, v101
	v_fmac_f32_e32 v112, v102, v102
	v_fmac_f32_e32 v112, v103, v103
	v_fmac_f32_e32 v112, v104, v104
	v_fmac_f32_e32 v112, v105, v105
	v_fmac_f32_e32 v112, v106, v106
	v_fmac_f32_e32 v112, v107, v107
	v_fmac_f32_e32 v112, v108, v108
	v_fmac_f32_e32 v112, v109, v109
	v_fmac_f32_e32 v112, v110, v110
	v_fmac_f32_e32 v112, v111, v111
	v_cvt_f32_i32_e32 v117, v42
	s_nop 0
	v_add_f32_dpp v113, v112, v112 quad_perm:[1,0,3,2] row_mask:0xf bank_mask:0xf
	v_mul_f32_e32 v118, v117, v20
	v_mul_f32_e32 v119, v117, v21
	v_add_f32_dpp v112, v113, v113 quad_perm:[2,3,0,1] row_mask:0xf bank_mask:0xf
	v_mul_f32_e32 v114, 0.15915494, v118
	v_mul_f32_e32 v115, 0.15915494, v119
	v_add_f32_dpp v113, v112, v112 row_half_mirror row_mask:0xf bank_mask:0xf
	v_floor_f32_e32 v114, v114
	v_floor_f32_e32 v115, v115
	v_fma_f32 v116, v113, s3, v24
	v_fma_f32 v118, v118, 0.15915494, -v114
	v_fma_f32 v119, v119, 0.15915494, -v115
	v_rsq_f32_e32 v116, v116
	v_sin_f32_e32 v120, v118
	v_cos_f32_e32 v121, v118
	v_sin_f32_e32 v122, v119
	v_cos_f32_e32 v123, v119
	v_mul_f32_e32 v100, v100, v116
	v_mul_f32_e32 v101, v101, v116
	v_mul_f32_e32 v102, v102, v116
	v_mul_f32_e32 v103, v103, v116
	v_mul_f32_e32 v104, v104, v116
	v_mul_f32_e32 v105, v105, v116
	v_mul_f32_e32 v106, v106, v116
	v_mul_f32_e32 v107, v107, v116
	v_mul_f32_e32 v108, v108, v116
	v_mul_f32_e32 v109, v109, v116
	v_mul_f32_e32 v110, v110, v116
	v_mul_f32_e32 v111, v111, v116
	v_mul_f32_e32 v100, v100, v8
	v_mul_f32_e32 v101, v101, v9
	v_mul_f32_e32 v102, v102, v10
	v_mul_f32_e32 v103, v103, v11
	v_mul_f32_e32 v104, v104, v12
	v_mul_f32_e32 v105, v105, v13
	v_mul_f32_e32 v106, v106, v14
	v_mul_f32_e32 v107, v107, v15
	v_mul_f32_e32 v108, v108, v16
	v_mul_f32_e32 v109, v109, v17
	v_mul_f32_e32 v110, v110, v18
	v_mul_f32_e32 v111, v111, v19
	v_mul_f32_e32 v124, v110, v120
	v_mul_f32_e32 v125, v111, v122
	v_mul_f32_e32 v126, v108, v120
	v_mul_f32_e32 v127, v109, v122
	v_fma_f32 v124, v108, v121, -v124
	v_fma_f32 v125, v109, v123, -v125
	v_fma_f32 v126, v110, v121, v126
	v_fma_f32 v127, v111, v123, v127
	v_cvt_pk_bf16_f32 v128, v100, v101
	v_cvt_pk_bf16_f32 v129, v102, v103
	v_cvt_pk_bf16_f32 v130, v104, v105
	v_cvt_pk_bf16_f32 v131, v106, v107
	v_cvt_pk_bf16_f32 v132, v124, v125
	v_cvt_pk_bf16_f32 v133, v126, v127
	global_store_dwordx4 v32, v[128:131], s[8:9]
	global_store_dword v33, v132, s[8:9] offset:128
	global_store_dword v33, v133, s[8:9] offset:160
	s_waitcnt vmcnt(11)
; DI bf16_t tobf(float a) { return (bf16_t)(pack2(a, 0.f) & 0xffffu); }
; template <int D, bool ROPE>
; DI void headnorm_phase(const bf16_t* src1, int ld1, int hs1, const bf16_t* src2, int ld2, int hs2, bf16_t* dst, int ldd, int hsd,
;                        const float* __restrict__ gain, int nrows, int nheads, const int* __restrict__ pos, float oscale) {
;     ...
;     for (int u = 0; u < U; ++u) {
;       float ss = 0.f;
; #pragma unroll
;       for (int m = 0; m < NM; ++m) ss += v[u][m] * v[u][m];
;       ss += __shfl_xor(ss, 1); ss += __shfl_xor(ss, 2); ss += __shfl_xor(ss, 4); ss += __shfl_xor(ss, 8);
;       const float rstd = rsqrtf(ss * (1.f / D) + EPS);
; #pragma unroll
;       for (int m = 0; m < NM; ++m) v[u][m] = v[u][m] * rstd * gn[m];
;       if (ROPE) {
;         const float ang = (float)pos[rowv[u]] * invf;
;         float rev = ang * 0.15915494309189535f;
;         rev = rev - floorf(rev);
;         const float sn = __builtin_amdgcn_sinf(rev), cs = __builtin_amdgcn_cosf(rev);
;         const float x1 = v[u][NM - 2], x2 = v[u][NM - 1];
;         v[u][NM - 2] = x1 * cs - x2 * sn;
;         v[u][NM - 1] = x2 * cs + x1 * sn;
;       }
;     }
; #pragma unroll
;     for (int u = 0; u < U; ++u)
; #pragma unroll
;       for (int m = 0; m < NM; ++m) dst[(size_t)rowv[u] * ldd + hdv[u] * hsd + s + 16 * m] = tobf(v[u][m]);
	v_lshlrev_b32_e32 v100, 16, v48
	v_and_b32_e32 v101, 0xffff0000, v48
	v_lshlrev_b32_e32 v102, 16, v49
	v_and_b32_e32 v103, 0xffff0000, v49
	v_lshlrev_b32_e32 v104, 16, v50
	v_and_b32_e32 v105, 0xffff0000, v50
	v_lshlrev_b32_e32 v106, 16, v51
	v_and_b32_e32 v107, 0xffff0000, v51
	v_lshlrev_b32_e32 v108, 16, v52
	v_and_b32_e32 v109, 0xffff0000, v52
	v_lshlrev_b32_e32 v110, 16, v53
	v_and_b32_e32 v111, 0xffff0000, v53
	v_mul_f32_e32 v112, v100, v100
	v_fmac_f32_e32 v112, v101, v101
	v_fmac_f32_e32 v112, v102, v102
	v_fmac_f32_e32 v112, v103, v103
	v_fmac_f32_e32 v112, v104, v104
	v_fmac_f32_e32 v112, v105, v105
	v_fmac_f32_e32 v112, v106, v106
	v_fmac_f32_e32 v112, v107, v107
	v_fmac_f32_e32 v112, v108, v108
	v_fmac_f32_e32 v112, v109, v109
	v_fmac_f32_e32 v112, v110, v110
	v_fmac_f32_e32 v112, v111, v111
	v_cvt_f32_i32_e32 v117, v54
	s_nop 0
	v_add_f32_dpp v113, v112, v112 quad_perm:[1,0,3,2] row_mask:0xf bank_mask:0xf
	v_mul_f32_e32 v118, v117, v20
	v_mul_f32_e32 v119, v117, v21
	v_add_f32_dpp v112, v113, v113 quad_perm:[2,3,0,1] row_mask:0xf bank_mask:0xf
	v_mul_f32_e32 v114, 0.15915494, v118
	v_mul_f32_e32 v115, 0.15915494, v119
	v_add_f32_dpp v113, v112, v112 row_half_mirror row_mask:0xf bank_mask:0xf
	v_floor_f32_e32 v114, v114
	v_floor_f32_e32 v115, v115
	v_fma_f32 v116, v113, s3, v24
	v_fma_f32 v118, v118, 0.15915494, -v114
	v_fma_f32 v119, v119, 0.15915494, -v115
	v_rsq_f32_e32 v116, v116
	v_sin_f32_e32 v120, v118
	v_cos_f32_e32 v121, v118
	v_sin_f32_e32 v122, v119
	v_cos_f32_e32 v123, v119
	v_mul_f32_e32 v100, v100, v116
	v_mul_f32_e32 v101, v101, v116
	v_mul_f32_e32 v102, v102, v116
	v_mul_f32_e32 v103, v103, v116
	v_mul_f32_e32 v104, v104, v116
	v_mul_f32_e32 v105, v105, v116
	v_mul_f32_e32 v106, v106, v116
	v_mul_f32_e32 v107, v107, v116
	v_mul_f32_e32 v108, v108, v116
	v_mul_f32_e32 v109, v109, v116
	v_mul_f32_e32 v110, v110, v116
	v_mul_f32_e32 v111, v111, v116
	v_mul_f32_e32 v100, v100, v8
	v_mul_f32_e32 v101, v101, v9
	v_mul_f32_e32 v102, v102, v10
	v_mul_f32_e32 v103, v103, v11
	v_mul_f32_e32 v104, v104, v12
	v_mul_f32_e32 v105, v105, v13
	v_mul_f32_e32 v106, v106, v14
	v_mul_f32_e32 v107, v107, v15
	v_mul_f32_e32 v108, v108, v16
	v_mul_f32_e32 v109, v109, v17
	v_mul_f32_e32 v110, v110, v18
	v_mul_f32_e32 v111, v111, v19
	v_mul_f32_e32 v124, v110, v120
	v_mul_f32_e32 v125, v111, v122
	v_mul_f32_e32 v126, v108, v120
	v_mul_f32_e32 v127, v109, v122
	v_fma_f32 v124, v108, v121, -v124
	v_fma_f32 v125, v109, v123, -v125
	v_fma_f32 v126, v110, v121, v126
	v_fma_f32 v127, v111, v123, v127
	v_cvt_pk_bf16_f32 v128, v100, v101
	v_cvt_pk_bf16_f32 v129, v102, v103
	v_cvt_pk_bf16_f32 v130, v104, v105
	v_cvt_pk_bf16_f32 v131, v106, v107
	v_cvt_pk_bf16_f32 v132, v124, v125
	v_cvt_pk_bf16_f32 v133, v126, v127
	global_store_dwordx4 v44, v[128:131], s[8:9]
	global_store_dword v45, v132, s[8:9] offset:128
	global_store_dword v45, v133, s[8:9] offset:160
	s_waitcnt vmcnt(10)
	v_lshlrev_b32_e32 v100, 16, v60
	v_and_b32_e32 v101, 0xffff0000, v60
	v_lshlrev_b32_e32 v102, 16, v61
	v_and_b32_e32 v103, 0xffff0000, v61
	v_lshlrev_b32_e32 v104, 16, v62
	v_and_b32_e32 v105, 0xffff0000, v62
	v_lshlrev_b32_e32 v106, 16, v63
	v_and_b32_e32 v107, 0xffff0000, v63
	v_lshlrev_b32_e32 v108, 16, v64
	v_and_b32_e32 v109, 0xffff0000, v64
	v_lshlrev_b32_e32 v110, 16, v65
	v_and_b32_e32 v111, 0xffff0000, v65
	v_mul_f32_e32 v112, v100, v100
	v_fmac_f32_e32 v112, v101, v101
	v_fmac_f32_e32 v112, v102, v102
	v_fmac_f32_e32 v112, v103, v103
	v_fmac_f32_e32 v112, v104, v104
	v_fmac_f32_e32 v112, v105, v105
	v_fmac_f32_e32 v112, v106, v106
	v_fmac_f32_e32 v112, v107, v107
	v_fmac_f32_e32 v112, v108, v108
	v_fmac_f32_e32 v112, v109, v109
	v_fmac_f32_e32 v112, v110, v110
	v_fmac_f32_e32 v112, v111, v111
	v_cvt_f32_i32_e32 v117, v66
	s_nop 0
	v_add_f32_dpp v113, v112, v112 quad_perm:[1,0,3,2] row_mask:0xf bank_mask:0xf
	v_mul_f32_e32 v118, v117, v20
	v_mul_f32_e32 v119, v117, v21
	v_add_f32_dpp v112, v113, v113 quad_perm:[2,3,0,1] row_mask:0xf bank_mask:0xf
	v_mul_f32_e32 v114, 0.15915494, v118
	v_mul_f32_e32 v115, 0.15915494, v119
	v_add_f32_dpp v113, v112, v112 row_half_mirror row_mask:0xf bank_mask:0xf
	v_floor_f32_e32 v114, v114
	v_floor_f32_e32 v115, v115
	v_fma_f32 v116, v113, s3, v24
	v_fma_f32 v118, v118, 0.15915494, -v114
	v_fma_f32 v119, v119, 0.15915494, -v115
	v_rsq_f32_e32 v116, v116
	v_sin_f32_e32 v120, v118
	v_cos_f32_e32 v121, v118
	v_sin_f32_e32 v122, v119
	v_cos_f32_e32 v123, v119
	v_mul_f32_e32 v100, v100, v116
	v_mul_f32_e32 v101, v101, v116
	v_mul_f32_e32 v102, v102, v116
	v_mul_f32_e32 v103, v103, v116
	v_mul_f32_e32 v104, v104, v116
	v_mul_f32_e32 v105, v105, v116
	v_mul_f32_e32 v106, v106, v116
	v_mul_f32_e32 v107, v107, v116
	v_mul_f32_e32 v108, v108, v116
	v_mul_f32_e32 v109, v109, v116
	v_mul_f32_e32 v110, v110, v116
	v_mul_f32_e32 v111, v111, v116
	v_mul_f32_e32 v100, v100, v8
	v_mul_f32_e32 v101, v101, v9
	v_mul_f32_e32 v102, v102, v10
	v_mul_f32_e32 v103, v103, v11
	v_mul_f32_e32 v104, v104, v12
	v_mul_f32_e32 v105, v105, v13
	v_mul_f32_e32 v106, v106, v14
	v_mul_f32_e32 v107, v107, v15
	v_mul_f32_e32 v108, v108, v16
	v_mul_f32_e32 v109, v109, v17
	v_mul_f32_e32 v110, v110, v18
	v_mul_f32_e32 v111, v111, v19
	v_mul_f32_e32 v124, v110, v120
	v_mul_f32_e32 v125, v111, v122
	v_mul_f32_e32 v126, v108, v120
	v_mul_f32_e32 v127, v109, v122
	v_fma_f32 v124, v108, v121, -v124
	v_fma_f32 v125, v109, v123, -v125
	v_fma_f32 v126, v110, v121, v126
	v_fma_f32 v127, v111, v123, v127
	v_cvt_pk_bf16_f32 v128, v100, v101
	v_cvt_pk_bf16_f32 v129, v102, v103
	v_cvt_pk_bf16_f32 v130, v104, v105
	v_cvt_pk_bf16_f32 v131, v106, v107
	v_cvt_pk_bf16_f32 v132, v124, v125
	v_cvt_pk_bf16_f32 v133, v126, v127
	global_store_dwordx4 v56, v[128:131], s[8:9]
	global_store_dword v57, v132, s[8:9] offset:128
	global_store_dword v57, v133, s[8:9] offset:160
	s_waitcnt vmcnt(9)
; DI bf16_t tobf(float a) { return (bf16_t)(pack2(a, 0.f) & 0xffffu); }
; DI void xcd_barrier(const XcdBarrier& b) {
;   asm volatile("s_waitcnt vmcnt(0)" ::: "memory");
;   __syncthreads();
;   if (threadIdx.x == 0) {
;     unsigned* bar = b.bar;
;     __builtin_amdgcn_s_waitcnt(0);
;     unsigned nloc = b.st[0], nx = b.st[1];
;     if (nloc == 0u) { xcd_barrier_complete(bar, b.x, nloc, nx); b.st[0] = nloc; b.st[1] = nx; }
; template <int D, bool ROPE>
; DI void headnorm_phase(const bf16_t* src1, int ld1, int hs1, const bf16_t* src2, int ld2, int hs2, bf16_t* dst, int ldd, int hsd,
;                        const float* __restrict__ gain, int nrows, int nheads, const int* __restrict__ pos, float oscale) {
;     ...
;     for (int u = 0; u < U; ++u) {
;       float ss = 0.f;
; #pragma unroll
;       for (int m = 0; m < NM; ++m) ss += v[u][m] * v[u][m];
;       ss += __shfl_xor(ss, 1); ss += __shfl_xor(ss, 2); ss += __shfl_xor(ss, 4); ss += __shfl_xor(ss, 8);
;       const float rstd = rsqrtf(ss * (1.f / D) + EPS);
; #pragma unroll
;       for (int m = 0; m < NM; ++m) v[u][m] = v[u][m] * rstd * gn[m];
;       if (ROPE) {
;         const float ang = (float)pos[rowv[u]] * invf;
;         float rev = ang * 0.15915494309189535f;
;         rev = rev - floorf(rev);
;         const float sn = __builtin_amdgcn_sinf(rev), cs = __builtin_amdgcn_cosf(rev);
;         const float x1 = v[u][NM - 2], x2 = v[u][NM - 1];
;         v[u][NM - 2] = x1 * cs - x2 * sn;
;         v[u][NM - 1] = x2 * cs + x1 * sn;
;       }
;     }
; #pragma unroll
;     for (int u = 0; u < U; ++u)
; #pragma unroll
;       for (int m = 0; m < NM; ++m) dst[(size_t)rowv[u] * ldd + hdv[u] * hsd + s + 16 * m] = tobf(v[u][m]);
	v_lshlrev_b32_e32 v100, 16, v72
	v_and_b32_e32 v101, 0xffff0000, v72
	v_lshlrev_b32_e32 v102, 16, v73
	v_and_b32_e32 v103, 0xffff0000, v73
	v_lshlrev_b32_e32 v104, 16, v74
	v_and_b32_e32 v105, 0xffff0000, v74
	v_lshlrev_b32_e32 v106, 16, v75
	v_and_b32_e32 v107, 0xffff0000, v75
	v_lshlrev_b32_e32 v108, 16, v76
	v_and_b32_e32 v109, 0xffff0000, v76
	v_lshlrev_b32_e32 v110, 16, v77
	v_and_b32_e32 v111, 0xffff0000, v77
	v_mul_f32_e32 v112, v100, v100
	v_fmac_f32_e32 v112, v101, v101
	v_fmac_f32_e32 v112, v102, v102
	v_fmac_f32_e32 v112, v103, v103
	v_fmac_f32_e32 v112, v104, v104
	v_fmac_f32_e32 v112, v105, v105
	v_fmac_f32_e32 v112, v106, v106
	v_fmac_f32_e32 v112, v107, v107
	v_fmac_f32_e32 v112, v108, v108
	v_fmac_f32_e32 v112, v109, v109
	v_fmac_f32_e32 v112, v110, v110
	v_fmac_f32_e32 v112, v111, v111
	v_cvt_f32_i32_e32 v117, v78
	s_nop 0
	v_add_f32_dpp v113, v112, v112 quad_perm:[1,0,3,2] row_mask:0xf bank_mask:0xf
	v_mul_f32_e32 v118, v117, v20
	v_mul_f32_e32 v119, v117, v21
	v_add_f32_dpp v112, v113, v113 quad_perm:[2,3,0,1] row_mask:0xf bank_mask:0xf
	v_mul_f32_e32 v114, 0.15915494, v118
	v_mul_f32_e32 v115, 0.15915494, v119
	v_add_f32_dpp v113, v112, v112 row_half_mirror row_mask:0xf bank_mask:0xf
	v_floor_f32_e32 v114, v114
	v_floor_f32_e32 v115, v115
	v_fma_f32 v116, v113, s3, v24
	v_fma_f32 v118, v118, 0.15915494, -v114
	v_fma_f32 v119, v119, 0.15915494, -v115
	v_rsq_f32_e32 v116, v116
	v_sin_f32_e32 v120, v118
	v_cos_f32_e32 v121, v118
	v_sin_f32_e32 v122, v119
	v_cos_f32_e32 v123, v119
	v_mul_f32_e32 v100, v100, v116
	v_mul_f32_e32 v101, v101, v116
	v_mul_f32_e32 v102, v102, v116
	v_mul_f32_e32 v103, v103, v116
	v_mul_f32_e32 v104, v104, v116
	v_mul_f32_e32 v105, v105, v116
	v_mul_f32_e32 v106, v106, v116
	v_mul_f32_e32 v107, v107, v116
	v_mul_f32_e32 v108, v108, v116
	v_mul_f32_e32 v109, v109, v116
	v_mul_f32_e32 v110, v110, v116
	v_mul_f32_e32 v111, v111, v116
	v_mul_f32_e32 v100, v100, v8
	v_mul_f32_e32 v101, v101, v9
	v_mul_f32_e32 v102, v102, v10
	v_mul_f32_e32 v103, v103, v11
	v_mul_f32_e32 v104, v104, v12
	v_mul_f32_e32 v105, v105, v13
	v_mul_f32_e32 v106, v106, v14
	v_mul_f32_e32 v107, v107, v15
	v_mul_f32_e32 v108, v108, v16
	v_mul_f32_e32 v109, v109, v17
	v_mul_f32_e32 v110, v110, v18
	v_mul_f32_e32 v111, v111, v19
	v_mul_f32_e32 v124, v110, v120
	v_mul_f32_e32 v125, v111, v122
	v_mul_f32_e32 v126, v108, v120
	v_mul_f32_e32 v127, v109, v122
	v_fma_f32 v124, v108, v121, -v124
	v_fma_f32 v125, v109, v123, -v125
	v_fma_f32 v126, v110, v121, v126
	v_fma_f32 v127, v111, v123, v127
	v_cvt_pk_bf16_f32 v128, v100, v101
	v_cvt_pk_bf16_f32 v129, v102, v103
	v_cvt_pk_bf16_f32 v130, v104, v105
	v_cvt_pk_bf16_f32 v131, v106, v107
	v_cvt_pk_bf16_f32 v132, v124, v125
	v_cvt_pk_bf16_f32 v133, v126, v127
	global_store_dwordx4 v68, v[128:131], s[8:9]
	global_store_dword v69, v132, s[8:9] offset:128
	global_store_dword v69, v133, s[8:9] offset:160
	s_add_i32 s1, s1, s2
	s_branch .Lhp_loop
.Lhp_done:
.LBB0_1112:
	s_or_b64 exec, exec, s[6:7]
	s_waitcnt vmcnt(0)
	s_barrier
	s_and_saveexec_b64 s[0:1], s[94:95]
	s_cbranch_execz .LBB0_1164
	v_mov_b32_e32 v0, 0
	s_waitcnt vmcnt(0) expcnt(0) lgkmcnt(0)
	ds_read_b32 v2, v0 offset:256
	ds_read_b32 v1, v0 offset:260
	s_waitcnt lgkmcnt(1)
	v_cmp_ne_u32_e32 vcc, 0, v2
	s_cbranch_vccnz .LBB0_1128
	v_readlane_b32 s2, v254, 4
	s_mul_i32 s4, s89, s2
	s_add_u32 s2, s86, 0xbfa0200
	s_addc_u32 s3, s87, 0
	s_add_u32 s6, s86, 0xbfa0400
	s_addc_u32 s7, s87, 0
	s_add_u32 s8, s86, 0xbfa0500
	s_addc_u32 s9, s87, 0
	s_add_u32 s10, s86, 0xbfa0600
	s_addc_u32 s11, s87, 0
	s_add_u32 s12, s86, 0xbfa0700
	s_addc_u32 s13, s87, 0
	s_add_u32 s24, s86, 0xbfa0800
	s_addc_u32 s25, s87, 0
	s_add_u32 s26, s86, 0xbfa0900
	s_addc_u32 s27, s87, 0
	s_add_u32 s28, s86, 0xbfa0a00
	s_addc_u32 s29, s87, 0
	s_add_u32 s30, s86, 0xbfa0b00
	s_addc_u32 s31, s87, 0
	s_add_u32 s34, s86, 0xbfa0c00
	s_addc_u32 s35, s87, 0
	s_add_u32 s36, s86, 0xbfa0d00
	s_addc_u32 s37, s87, 0
	s_add_u32 s38, s86, 0xbfa0e00
	s_addc_u32 s39, s87, 0
	s_add_u32 s40, s86, 0xbfa0f00
	s_addc_u32 s41, s87, 0
	s_add_u32 s44, s86, 0xbfa1000
	s_addc_u32 s45, s87, 0
	s_add_u32 s62, s86, 0xbfa1100
	s_addc_u32 s63, s87, 0
	s_add_u32 s64, s86, 0xbfa1200
	s_addc_u32 s65, s87, 0
	s_add_u32 s66, s86, 0xbfa1300
	s_mul_i32 s4, s4, s88
	s_addc_u32 s67, s87, 0
	s_mov_b32 s5, 1
	s_branch .LBB0_1116

; DI unsigned xb_ld(unsigned* p) { return __hip_atomic_load(p, __ATOMIC_RELAXED, __HIP_MEMORY_SCOPE_AGENT); }
; DI unsigned xb_add(unsigned* p, unsigned v) { return __hip_atomic_fetch_add(p, v, __ATOMIC_RELAXED, __HIP_MEMORY_SCOPE_AGENT); }
; #define XB_SPIN(cond, bar) do { unsigned _sp = 0; while (cond) { __builtin_amdgcn_s_sleep(1); \
;     if ((++_sp & 255u) == 0u) { if (xb_ld(&(bar)[XB_TMO])) break; if (_sp > XB_SPIN_CAP) { atomicAdd(&(bar)[XB_TMO], 1u); break; } } } } while (0)
; DI void xcd_barrier(const XcdBarrier& b) {
;     ...
;     if (old + 1u == (gen + 1u) * nloc) {
;       __builtin_amdgcn_fence(__ATOMIC_RELEASE, "agent");
;       asm volatile("s_waitcnt vmcnt(0)" ::: "memory");
;       const unsigned og = xb_add(&bar[XB_TOP], 1u);
;       const unsigned tg = og / nx;
;       if (og + 1u == (tg + 1u) * nx) xb_add(&bar[XB_TOPGEN], 1u);
;       else XB_SPIN(xb_ld(&bar[XB_TOPGEN]) == tg, bar);
.LBB0_1144:
	s_andn2_saveexec_b64 s[4:5], s[6:7]
	s_cbranch_execz .LBB0_1164
	s_mov_b64 s[6:7], exec
	v_mov_b32_e32 v255, 0
	ds_read_b32 v255, v255 offset:264
	s_waitcnt lgkmcnt(0)
	v_cmp_ne_u32_e32 vcc, 0, v255
	s_cbranch_vccnz .LBB0_1161
	buffer_wbl2 sc1
	s_waitcnt lgkmcnt(0)
	s_waitcnt vmcnt(0)
	v_mbcnt_lo_u32_b32 v0, s6, 0
	v_mbcnt_hi_u32_b32 v0, s7, v0
	v_cmp_eq_u32_e32 vcc, 0, v0
	s_and_saveexec_b64 s[8:9], vcc
	s_cbranch_execz .LBB0_1147
	s_bcnt1_i32_b64 s4, s[6:7]
	v_mov_b32_e32 v2, 0xbfa3000
	v_mov_b32_e32 v3, s4
	global_atomic_add v2, v2, v3, s[86:87] offset:1024 sc0
.LBB0_1147:
	s_or_b64 exec, exec, s[8:9]
	v_cvt_f32_u32_e32 v3, v1
	s_waitcnt vmcnt(0)
	v_readfirstlane_b32 s4, v2
	s_add_u32 s8, s86, 0xbfa3500
	s_addc_u32 s9, s87, 0
	v_rcp_iflag_f32_e32 v3, v3
	v_add_u32_e32 v0, s4, v0
	v_add_u32_e32 v4, 1, v0
	s_mov_b64 s[10:11], -1
	v_mul_f32_e32 v2, 0x4f7ffffe, v3
	v_cvt_u32_f32_e32 v2, v2
	v_sub_u32_e32 v3, 0, v1
	v_mul_lo_u32 v3, v3, v2
	v_mul_hi_u32 v3, v2, v3
	v_add_u32_e32 v2, v2, v3
	v_mul_hi_u32 v2, v0, v2
	v_mul_lo_u32 v3, v2, v1
	v_sub_u32_e32 v0, v0, v3
	v_add_u32_e32 v5, 1, v2
	v_cmp_ge_u32_e32 vcc, v0, v1
	v_sub_u32_e32 v3, v0, v1
	s_nop 0
	v_cndmask_b32_e32 v2, v2, v5, vcc
	v_cndmask_b32_e32 v0, v0, v3, vcc
	v_add_u32_e32 v3, 1, v2
	v_cmp_ge_u32_e32 vcc, v0, v1
	s_nop 1
	v_cndmask_b32_e32 v2, v2, v3, vcc
	v_mul_lo_u32 v0, v1, v2
	v_add_u32_e32 v0, v0, v1
	v_cmp_ne_u32_e32 vcc, v4, v0
	v_mov_b64_e32 v[0:1], s[8:9]
	s_and_saveexec_b64 s[6:7], vcc
	s_cbranch_execz .LBB0_1159
	v_mov_b32_e32 v0, 0
	global_load_dword v1, v0, s[8:9] sc1
	s_mov_b64 s[24:25], 0
	s_waitcnt vmcnt(0)
	v_cmp_eq_u32_e32 vcc, v1, v2
	s_and_saveexec_b64 s[12:13], vcc
	s_cbranch_execz .LBB0_1158
	s_add_u32 s10, s86, 0xbfa0200
	s_addc_u32 s11, s87, 0
	s_mov_b32 s4, 1
	s_branch .LBB0_1151

; template <int DQK, int MODE, bool QN, bool KN> ...
;     ...
;   const int tid = launder_tid(), lane = tid & 63, wave = tid >> 6, r = lane & 31, h = lane >> 5;
;   const int qrow = q0 + wave * 32 + r;
;   const int qwmax = q0 + wave * 32 + 31;
;   bf16x8 qf[NS];
; #pragma unroll
;   for (int s = 0; s < NS; ++s) qf[s] = *(const bf16x8*)(Q + (size_t)(wave * 32 + r) * ldq + 16 * s + 8 * h);
;   if (QN) {
;     float qv[NS][8];
;     float ss = 0.f;
; #pragma unroll
;     for (int s = 0; s < NS; ++s)
; #pragma unroll
;       for (int j = 0; j < 8; ++j) { qv[s][j] = bf2f((bf16_t)qf[s][j]); ss += qv[s][j] * qv[s][j]; }
;     ss += __shfl_xor(ss, 32);
;     const float rstd = rsqrtf(ss * (1.f / DQK) + EPS) * oscale;
; #pragma unroll
;     for (int s = 0; s < NS; ++s) {
;       const f32x4 g0 = *(const f32x4*)(gq + 16 * s + 8 * h), g1 = *(const f32x4*)(gq + 16 * s + 8 * h + 4);
; #pragma unroll
;       for (int j = 0; j < 4; ++j) { qv[s][j] *= rstd * g0[j]; qv[s][4 + j] *= rstd * g1[j]; }
;     }
;     if (DQK == 96) {
;       const float pf_ = (float)qpos[wave * 32 + r];
; #pragma unroll
; template <int LAYER>
; DI void attn_phase(const Params& p, char* smem) {
;     ...
;   const int xcd = (int)(blockIdx.x & 7), lb = (int)(blockIdx.x >> 3), L = (int)(gridDim.x >> 3);
;   for (int j = lb; j < 192 + 64; j += L) {
;     if (j < 192) {
;       const int hl = j >> 4, qi = j & 15, qt = ((j / L) & 1) ? (15 - qi) : qi, bh = hl * 8 + xcd, b = bh / 12, hd = bh % 12, q0 = qt * 256;
;       const size_t tok0 = (size_t)b * SEQ;
;       bf16_t* O = mix + (tok0 + q0) * DM + hd * 64;
;       if (LAYER == 0) {
;         const bf16_t* P = (const bf16_t*)(ws + O_P);
;         attn_item<64, 2, false, false>(P + (tok0 + q0) * 2560 + hd * 64, 2560, P + tok0 * 2560 + 768 + hd * 64, 2560, P + tok0 * 2560 + 1536 + hd * 64, 2560,
;                                        q0, q0 / 64 + 4, O, 0.125f, smem, nullptr, 1.f, nullptr, nullptr);
;       } else {
;         const bf16_t* Qb = (const bf16_t*)(ws + O_QB);
;         const bf16_t* Kn = (const bf16_t*)(ws + O_KN);
;         const bf16_t* V1 = (const bf16_t*)(ws + O_V1);
;         attn_item<96, 1, true, false>(Qb + (tok0 + q0) * 1152 + hd * 96, 1152, Kn + tok0 * 1152 + hd * 96, 1152, V1 + tok0 * 768 + hd * 64, 768,
;                                       q0, q0 / 64 + 4, O, 1.f, smem, p.mla_g_qn, 0.14724138410008716f, p.pos + tok0 + q0, p.mla_g_kn);
.LBB0_1194:
	s_and_b64 vcc, exec, s[0:1]
	s_cbranch_vccz .LBB0_1167
	v_readlane_b32 s0, v254, 22
	s_mul_hi_u32 s0, s54, s0
	s_mul_i32 s1, s0, s42
	s_sub_i32 s1, s54, s1
	s_add_i32 s2, s0, 1
	s_sub_i32 s3, s1, s42
	s_cmp_ge_u32 s1, s42
	s_cselect_b32 s0, s2, s0
	s_cselect_b32 s1, s3, s1
	s_add_i32 s2, s0, 1
	s_cmp_ge_u32 s1, s42
	s_cselect_b32 s0, s2, s0
	s_lshr_b32 s1, s54, 1
	s_and_b32 s1, s1, 0x78
	s_or_b32 s1, s1, s52
	s_mov_b32 s4, s52
	s_lshr_b32 s5, s54, 4
	s_lshl_b32 s1, s54, 8
	s_and_b32 s1, s1, 0xf00
	s_and_b32 s0, s0, 1
	s_xor_b32 s2, s1, 0xf00
	s_cmp_eq_u32 s0, 0
	s_cselect_b32 s16, s1, s2
	s_lshl_b32 s0, s4, 12
	s_or_b32 s6, s16, s0
	s_lshl_b32 s44, s5, 6
	s_mul_i32 s3, s6, 0x900
	s_mul_hi_u32 s2, s6, 0x900
	s_add_u32 s10, s20, s3
	s_addc_u32 s11, s21, s2
	s_mul_i32 s2, s5, 0x60
	s_mov_b32 s3, s7
	s_lshl_b64 s[2:3], s[2:3], 1
	s_add_u32 s12, s10, s2
	s_addc_u32 s13, s11, s3
	s_mul_i32 s10, s4, 0x900000
	s_mul_hi_u32 s11, s0, 0x900
	s_add_u32 s10, s14, s10
	s_addc_u32 s11, s15, s11
	s_add_u32 s2, s10, s2
	s_addc_u32 s3, s11, s3
	s_mul_i32 s4, s4, 0x600000
	s_mul_hi_u32 s10, s0, 0x600
	s_add_u32 s4, s22, s4
	s_addc_u32 s11, s23, s10
	s_lshl_b32 s5, s5, 7
	s_add_u32 s10, s4, s5
	s_mov_b32 s1, s7
	s_addc_u32 s11, s11, 0
	s_lshr_b32 s4, s16, 6
	s_add_i32 s4, s4, 4
	s_lshl_b64 s[0:1], s[0:1], 2
	s_add_u32 s0, s48, s0
	v_mov_b32_e32 v54, v212
	s_addc_u32 s1, s49, s1
	s_lshl_b32 s5, s16, 2
	s_add_u32 s0, s0, s5
	v_ashrrev_i32_e32 v0, 1, v54
	v_bfi_b32 v216, s27, v0, v54
	s_addc_u32 s1, s1, 0
	v_ashrrev_i32_e32 v217, 31, v216
	v_lshl_add_u64 v[2:3], v[216:217], 2, s[0:1]
	global_load_dword v58, v[2:3], off
	s_waitcnt vmcnt(9)
	v_bfe_u32 v112, v54, 5, 1
	v_lshlrev_b32_e32 v69, 3, v112
	v_cvt_f32_ubyte0_e32 v47, v69
	v_or_b32_e32 v48, 1, v69
	v_cmp_lt_i32_e32 vcc, v227, v228
	v_mul_f32_e32 v49, 0xbf549a78, v47
	v_cvt_f32_ubyte0_e32 v48, v48
	v_cndmask_b32_e32 v2, v226, v227, vcc
	v_cmp_gt_f32_e32 vcc, s38, v49
	v_mul_f32_e32 v50, 0xbf549a78, v48
	v_cmp_gt_f32_e64 s[0:1], s38, v50
	v_cndmask_b32_e32 v49, 0, v232, vcc
	v_fmac_f32_e32 v49, 0xbf549a78, v47
	v_cndmask_b32_e64 v47, 0, v232, s[0:1]
	v_fmac_f32_e32 v47, 0xbf549a78, v48
	v_exp_f32_e32 v47, v47
	v_and_b32_e32 v46, 0xffffffe0, v0
	v_exp_f32_e32 v49, v49
	v_cndmask_b32_e64 v50, 0, v233, s[0:1]
	v_ldexp_f32 v60, v47, v50
	v_add_u32_e32 v236, s16, v46
	v_mov_b64_e32 v[46:47], s[12:13]
	v_lshlrev_b32_e32 v0, 4, v112
	v_mad_i64_i32 v[46:47], s[0:1], v216, s36, v[46:47]
	v_lshlrev_b32_e32 v113, 5, v112
	v_cndmask_b32_e32 v48, 0, v233, vcc
	v_lshl_add_u64 v[56:57], v[46:47], 0, v[0:1]
	v_lshlrev_b32_e32 v235, 2, v2
	global_load_dwordx4 v[42:45], v113, s[80:81]
	global_load_dwordx4 v[38:41], v113, s[80:81] offset:64
	global_load_dwordx4 v[34:37], v113, s[80:81] offset:80
	global_load_dwordx4 v[30:33], v113, s[80:81] offset:128
	global_load_dwordx4 v[26:29], v113, s[80:81] offset:144
	global_load_dwordx4 v[22:25], v113, s[80:81] offset:192
	global_load_dwordx4 v[18:21], v113, s[80:81] offset:208
	global_load_dwordx4 v[14:17], v113, s[80:81] offset:256
	global_load_dwordx4 v[10:13], v113, s[80:81] offset:272
	global_load_dwordx4 v[6:9], v113, s[80:81] offset:320
	global_load_dwordx4 v[2:5], v113, s[80:81] offset:336
	v_ldexp_f32 v59, v49, v48
	global_load_dwordx4 v[50:53], v[56:57], off
	global_load_dwordx4 v[46:49], v[56:57], off offset:32
	global_load_dwordx4 v[102:105], v[56:57], off offset:64
	global_load_dwordx4 v[94:97], v[56:57], off offset:96
	global_load_dwordx4 v[84:87], v[56:57], off offset:128
	global_load_dwordx4 v[88:91], v[56:57], off offset:160
	v_and_b32_e32 v55, 31, v54
	v_ashrrev_i32_e32 v241, 3, v54
	s_lshr_b32 s12, s4, 1
	s_add_i32 s13, s12, -1
	v_or_b32_e32 v237, v236, v55
	s_mov_b32 s45, 3
	v_or_b32_e32 v243, 31, v236
	v_lshlrev_b32_e32 v247, 2, v112
	v_mov_b32_e32 v252, 0xff800000
	v_mov_b32_e32 v253, 0
	s_movk_i32 s53, 0xff
	s_waitcnt vmcnt(17)
	v_cvt_f32_i32_e32 v71, v58
	v_mul_f32_e32 v57, v60, v71
	v_mul_f32_e32 v56, v59, v71
	v_mul_f32_e32 v59, 0.15915494, v57
	v_floor_f32_e32 v59, v59
	v_fma_f32 v59, v57, 0.15915494, -v59
	v_or_b32_e32 v57, 2, v69
	v_cvt_f32_ubyte0_e32 v57, v57
	v_mul_f32_e32 v60, 0xbf549a78, v57
	v_cmp_gt_f32_e32 vcc, s38, v60
	v_mul_f32_e32 v58, 0.15915494, v56
	v_floor_f32_e32 v58, v58
	v_cndmask_b32_e32 v60, 0, v232, vcc
	v_fmac_f32_e32 v60, 0xbf549a78, v57
	v_exp_f32_e32 v60, v60
	v_cndmask_b32_e32 v61, 0, v233, vcc
	v_fma_f32 v58, v56, 0.15915494, -v58
	v_sin_f32_e32 v56, v58
	v_ldexp_f32 v60, v60, v61
	v_mul_f32_e32 v60, v60, v71
	v_mul_f32_e32 v61, 0.15915494, v60
	v_floor_f32_e32 v61, v61
	v_fma_f32 v61, v60, 0.15915494, -v61
	v_or_b32_e32 v60, 3, v69
	v_cvt_f32_ubyte0_e32 v60, v60
	v_mul_f32_e32 v62, 0xbf549a78, v60
	v_cmp_gt_f32_e32 vcc, s38, v62
	s_waitcnt vmcnt(3)
	v_and_b32_e32 v99, 0xffff0000, v104
	v_lshlrev_b32_e32 v98, 16, v104
	v_cndmask_b32_e32 v62, 0, v232, vcc
	v_fmac_f32_e32 v62, 0xbf549a78, v60
	v_exp_f32_e32 v63, v62
	v_sin_f32_e32 v60, v61
	v_cos_f32_e32 v62, v61
	v_cndmask_b32_e32 v61, 0, v233, vcc
	v_ldexp_f32 v61, v63, v61
	v_mul_f32_e32 v61, v61, v71
	v_mul_f32_e32 v63, 0.15915494, v61
	v_floor_f32_e32 v63, v63
	v_fma_f32 v63, v61, 0.15915494, -v63
	v_or_b32_e32 v61, 4, v69
	v_cvt_f32_ubyte0_e32 v61, v61
	v_mul_f32_e32 v64, 0xbf549a78, v61
	v_cmp_gt_f32_e32 vcc, s38, v64
	s_waitcnt vmcnt(1)
	v_and_b32_e32 v75, 0xffff0000, v87
	v_lshlrev_b32_e32 v74, 16, v87
	v_cndmask_b32_e32 v64, 0, v232, vcc
	v_fmac_f32_e32 v64, 0xbf549a78, v61
	v_exp_f32_e32 v64, v64
	v_cndmask_b32_e32 v65, 0, v233, vcc
	s_waitcnt vmcnt(0)
; DI float bf2f(bf16_t v) { return __uint_as_float(((unsigned)v) << 16); }
; template <int DQK, int MODE, bool QN, bool KN> ...
;     ...
;   if (QN) {
;     float qv[NS][8];
;     float ss = 0.f;
; #pragma unroll
;     for (int s = 0; s < NS; ++s)
; #pragma unroll
;       for (int j = 0; j < 8; ++j) { qv[s][j] = bf2f((bf16_t)qf[s][j]); ss += qv[s][j] * qv[s][j]; }
;     ss += __shfl_xor(ss, 32);
;     const float rstd = rsqrtf(ss * (1.f / DQK) + EPS) * oscale;
; #pragma unroll
;     for (int s = 0; s < NS; ++s) {
;       const f32x4 g0 = *(const f32x4*)(gq + 16 * s + 8 * h), g1 = *(const f32x4*)(gq + 16 * s + 8 * h + 4);
; #pragma unroll
;       for (int j = 0; j < 4; ++j) { qv[s][j] *= rstd * g0[j]; qv[s][4 + j] *= rstd * g1[j]; }
;     }
;     if (DQK == 96) {
;       const float pf_ = (float)qpos[wave * 32 + r];
; #pragma unroll
;       for (int j = 0; j < 8; ++j) {
;         const float ang = pf_ * exp2f(-(float)(8 * h + j) * (13.287712379549449f / 16.f));
;         float rev = ang * 0.15915494309189535f; rev = rev - floorf(rev);
;         const float sn = __builtin_amdgcn_sinf(rev), cs = __builtin_amdgcn_cosf(rev);
	v_and_b32_e32 v73, 0xffff0000, v91
	v_and_b32_e32 v81, 0xffff0000, v86
	v_ldexp_f32 v64, v64, v65
	v_mul_f32_e32 v64, v64, v71
	v_mul_f32_e32 v65, 0.15915494, v64
	v_floor_f32_e32 v65, v65
	v_fma_f32 v65, v64, 0.15915494, -v65
	v_or_b32_e32 v64, 5, v69
	v_cvt_f32_ubyte0_e32 v64, v64
	v_mul_f32_e32 v66, 0xbf549a78, v64
	v_cmp_gt_f32_e32 vcc, s38, v66
	v_lshlrev_b32_e32 v80, 16, v86
	v_and_b32_e32 v77, 0xffff0000, v90
	v_cndmask_b32_e32 v66, 0, v232, vcc
	v_fmac_f32_e32 v66, 0xbf549a78, v64
	v_exp_f32_e32 v67, v66
	v_sin_f32_e32 v64, v65
	v_cos_f32_e32 v66, v65
	v_cndmask_b32_e32 v65, 0, v233, vcc
	v_ldexp_f32 v65, v67, v65
	v_mul_f32_e32 v65, v65, v71
	v_mul_f32_e32 v67, 0.15915494, v65
	v_floor_f32_e32 v67, v67
	v_fma_f32 v67, v65, 0.15915494, -v67
	v_or_b32_e32 v65, 6, v69
	v_cvt_f32_ubyte0_e32 v65, v65
	v_or_b32_e32 v69, 7, v69
	v_mul_f32_e32 v68, 0xbf549a78, v65
	v_cvt_f32_ubyte0_e32 v69, v69
	v_cmp_gt_f32_e32 vcc, s38, v68
	v_mul_f32_e32 v72, 0xbf549a78, v69
	v_lshlrev_b32_e32 v76, 16, v90
	v_cndmask_b32_e32 v68, 0, v232, vcc
	v_cndmask_b32_e32 v70, 0, v233, vcc
	v_cmp_gt_f32_e32 vcc, s38, v72
	v_and_b32_e32 v83, 0xffff0000, v85
	v_lshlrev_b32_e32 v82, 16, v85
	v_cndmask_b32_e32 v72, 0, v232, vcc
	v_fmac_f32_e32 v72, 0xbf549a78, v69
	v_exp_f32_e32 v69, v72
	v_lshlrev_b32_e32 v72, 16, v91
	v_and_b32_e32 v79, 0xffff0000, v89
	v_lshlrev_b32_e32 v78, 16, v89
	v_and_b32_e32 v87, 0xffff0000, v84
	v_lshlrev_b32_e32 v86, 16, v84
	v_and_b32_e32 v85, 0xffff0000, v88
	v_lshlrev_b32_e32 v84, 16, v88
	v_and_b32_e32 v89, 0xffff0000, v97
	v_lshlrev_b32_e32 v88, 16, v97
	v_and_b32_e32 v91, 0xffff0000, v96
	v_lshlrev_b32_e32 v90, 16, v96
	v_and_b32_e32 v97, 0xffff0000, v105
	v_lshlrev_b32_e32 v96, 16, v105
	v_and_b32_e32 v105, 0xffff0000, v49
	v_lshlrev_b32_e32 v104, 16, v49
	v_and_b32_e32 v107, 0xffff0000, v48
	v_lshlrev_b32_e32 v106, 16, v48
	v_and_b32_e32 v109, 0xffff0000, v47
	v_lshlrev_b32_e32 v108, 16, v47
	v_and_b32_e32 v111, 0xffff0000, v46
	v_lshlrev_b32_e32 v110, 16, v46
	global_load_dwordx4 v[46:49], v113, s[80:81] offset:16
	v_and_b32_e32 v165, 0xffff0000, v50
	v_lshlrev_b32_e32 v164, 16, v50
	v_and_b32_e32 v161, 0xffff0000, v51
	v_lshlrev_b32_e32 v160, 16, v51
	v_pk_mul_f32 v[50:51], v[164:165], v[164:165]
	v_pk_mul_f32 v[162:163], v[160:161], v[160:161]
	v_add_f32_e32 v50, v50, v51
	v_and_b32_e32 v159, 0xffff0000, v52
	v_lshlrev_b32_e32 v158, 16, v52
	v_add_f32_e32 v50, v162, v50
	v_and_b32_e32 v155, 0xffff0000, v53
	v_lshlrev_b32_e32 v154, 16, v53
	v_pk_mul_f32 v[52:53], v[158:159], v[158:159]
	v_add_f32_e32 v50, v163, v50
	v_add_f32_e32 v50, v52, v50
	v_pk_mul_f32 v[156:157], v[154:155], v[154:155]
	v_add_f32_e32 v50, v53, v50
	v_add_f32_e32 v50, v156, v50
	v_pk_mul_f32 v[152:153], v[110:111], v[110:111]
	v_add_f32_e32 v50, v157, v50
	v_add_f32_e32 v50, v152, v50
	v_pk_mul_f32 v[150:151], v[108:109], v[108:109]
	v_add_f32_e32 v50, v153, v50
	v_add_f32_e32 v50, v150, v50
	v_pk_mul_f32 v[148:149], v[106:107], v[106:107]
	v_add_f32_e32 v50, v151, v50
	v_add_f32_e32 v50, v148, v50
	v_pk_mul_f32 v[146:147], v[104:105], v[104:105]
	v_add_f32_e32 v50, v149, v50
	v_and_b32_e32 v101, 0xffff0000, v103
	v_lshlrev_b32_e32 v100, 16, v103
	v_and_b32_e32 v103, 0xffff0000, v102
	v_lshlrev_b32_e32 v102, 16, v102
	v_add_f32_e32 v50, v146, v50
	v_pk_mul_f32 v[144:145], v[102:103], v[102:103]
	v_add_f32_e32 v50, v147, v50
	v_add_f32_e32 v50, v144, v50
	v_pk_mul_f32 v[142:143], v[100:101], v[100:101]
	v_add_f32_e32 v50, v145, v50
	v_add_f32_e32 v50, v142, v50
	v_pk_mul_f32 v[140:141], v[98:99], v[98:99]
	v_add_f32_e32 v50, v143, v50
	v_add_f32_e32 v50, v140, v50
	v_pk_mul_f32 v[138:139], v[96:97], v[96:97]
	v_add_f32_e32 v50, v141, v50
	v_and_b32_e32 v93, 0xffff0000, v95
	v_lshlrev_b32_e32 v92, 16, v95
	v_and_b32_e32 v95, 0xffff0000, v94
	v_lshlrev_b32_e32 v94, 16, v94
	v_add_f32_e32 v50, v138, v50
	v_pk_mul_f32 v[136:137], v[94:95], v[94:95]
	v_add_f32_e32 v50, v139, v50
	v_add_f32_e32 v50, v136, v50
	v_pk_mul_f32 v[134:135], v[92:93], v[92:93]
	v_add_f32_e32 v50, v137, v50
	v_add_f32_e32 v50, v134, v50
	v_pk_mul_f32 v[132:133], v[90:91], v[90:91]
	v_add_f32_e32 v50, v135, v50
	v_add_f32_e32 v50, v132, v50
	v_pk_mul_f32 v[130:131], v[88:89], v[88:89]
	v_add_f32_e32 v50, v133, v50
	v_add_f32_e32 v50, v130, v50
	v_pk_mul_f32 v[126:127], v[86:87], v[86:87]
	v_add_f32_e32 v50, v131, v50
	v_add_f32_e32 v50, v126, v50
	v_pk_mul_f32 v[122:123], v[82:83], v[82:83]
	v_add_f32_e32 v50, v127, v50
	v_add_f32_e32 v50, v122, v50
	v_pk_mul_f32 v[118:119], v[80:81], v[80:81]
	v_add_f32_e32 v50, v123, v50
	v_add_f32_e32 v50, v118, v50
	v_pk_mul_f32 v[114:115], v[74:75], v[74:75]
	v_add_f32_e32 v50, v119, v50
	v_add_f32_e32 v50, v114, v50
	v_pk_mul_f32 v[128:129], v[84:85], v[84:85]
	v_add_f32_e32 v50, v115, v50
	v_add_f32_e32 v50, v128, v50
	v_pk_mul_f32 v[124:125], v[78:79], v[78:79]
	v_add_f32_e32 v50, v129, v50
	v_add_f32_e32 v50, v124, v50
	v_pk_mul_f32 v[120:121], v[76:77], v[76:77]
	v_add_f32_e32 v50, v125, v50
	v_add_f32_e32 v50, v120, v50
	v_pk_mul_f32 v[116:117], v[72:73], v[72:73]
	v_add_f32_e32 v50, v121, v50
	v_add_f32_e32 v50, v116, v50
	v_add_f32_e32 v50, v117, v50
	ds_bpermute_b32 v51, v235, v50
	v_fmac_f32_e32 v68, 0xbf549a78, v65
	v_cndmask_b32_e32 v166, 0, v233, vcc
	v_exp_f32_e32 v68, v68
	v_ldexp_f32 v52, v69, v166
	s_waitcnt lgkmcnt(0)
; DI unsigned pack2(float a, float b) { bf2_t v = __builtin_convertvector((f32x2){a, b}, bf2_t); return __builtin_bit_cast(unsigned, v); }
; template <int DQK, int MODE, bool QN, bool KN> ...
;     ...
;     const float rstd = rsqrtf(ss * (1.f / DQK) + EPS) * oscale;
; #pragma unroll
;     for (int s = 0; s < NS; ++s) {
;       const f32x4 g0 = *(const f32x4*)(gq + 16 * s + 8 * h), g1 = *(const f32x4*)(gq + 16 * s + 8 * h + 4);
; #pragma unroll
;       for (int j = 0; j < 4; ++j) { qv[s][j] *= rstd * g0[j]; qv[s][4 + j] *= rstd * g1[j]; }
;     }
;     if (DQK == 96) {
;       const float pf_ = (float)qpos[wave * 32 + r];
; #pragma unroll
;       for (int j = 0; j < 8; ++j) {
;         const float ang = pf_ * exp2f(-(float)(8 * h + j) * (13.287712379549449f / 16.f));
;         float rev = ang * 0.15915494309189535f; rev = rev - floorf(rev);
;         const float sn = __builtin_amdgcn_sinf(rev), cs = __builtin_amdgcn_cosf(rev);
;         const float x1 = qv[NS - 2][j], x2 = qv[NS - 1][j];
;         qv[NS - 2][j] = x1 * cs - x2 * sn; qv[NS - 1][j] = x2 * cs + x1 * sn;
;       }
;     }
; #pragma unroll
;     for (int s = 0; s < NS; ++s) {
;       u32x4 w; w.x = pack2(qv[s][0], qv[s][1]); w.y = pack2(qv[s][2], qv[s][3]); w.z = pack2(qv[s][4], qv[s][5]); w.w = pack2(qv[s][6], qv[s][7]);
;       qf[s] = __builtin_bit_cast(bf16x8, w);
;     }
;   }
;   f32x4 gk0 = {1.f, 1.f, 1.f, 1.f}, gk1 = {1.f, 1.f, 1.f, 1.f};
;   if (KN) { gk0 = *(const f32x4*)(gk + (tid & 7) * 8); gk1 = *(const f32x4*)(gk + (tid & 7) * 8 + 4); }
;   float sbound = 0.f; bool fixed_shift = false;
;   if (MODE != 2 && QN) {
;     float gqm = 0.f, gkm = 0.f;
; #pragma unroll
;     for (int s = 0; s < NS; ++s)
; #pragma unroll
;       for (int j = 0; j < 8; ++j) { gqm = fmaxf(gqm, fabsf(gq[16 * s + 8 * h + j])); gkm = fmaxf(gkm, fabsf(gk[16 * s + 8 * h + j])); }
;     gqm = fmaxf(gqm, __shfl_xor(gqm, 32)); gkm = fmaxf(gkm, __shfl_xor(gkm, 32));
	v_add_f32_e32 v50, v50, v51
	v_fmamk_f32 v50, v50, 0x3c2aaaab, v214
	v_mul_f32_e32 v51, 0x4b800000, v50
	v_cmp_gt_f32_e32 vcc, s28, v50
	v_mul_f32_e32 v52, v52, v71
	v_mul_f32_e32 v53, 0.15915494, v52
	v_cndmask_b32_e32 v50, v50, v51, vcc
	v_rsq_f32_e32 v50, v50
	v_floor_f32_e32 v53, v53
	v_ldexp_f32 v68, v68, v70
	v_fma_f32 v51, v52, 0.15915494, -v53
	v_mul_f32_e32 v68, v68, v71
	v_sin_f32_e32 v69, v51
	v_cos_f32_e32 v71, v51
	v_mul_f32_e32 v51, 0x45800000, v50
	v_cndmask_b32_e32 v50, v50, v51, vcc
	v_mul_f32_e32 v126, 0x3e16c672, v50
	global_load_dwordx4 v[50:53], v113, s[82:83]
	v_pk_mul_f32 v[114:115], v[42:43], v[126:127] op_sel_hi:[1,0]
	s_waitcnt vmcnt(1)
	v_pk_mul_f32 v[118:119], v[46:47], v[126:127] op_sel_hi:[1,0]
	v_pk_mul_f32 v[128:129], v[114:115], v[164:165]
	global_load_dwordx4 v[114:117], v113, s[82:83] offset:16
	v_pk_mul_f32 v[130:131], v[118:119], v[158:159]
	v_pk_mul_f32 v[118:119], v[44:45], v[126:127] op_sel_hi:[1,0]
	v_pk_mul_f32 v[122:123], v[38:39], v[126:127] op_sel_hi:[1,0]
	v_pk_mul_f32 v[132:133], v[118:119], v[160:161]
	v_pk_mul_f32 v[118:119], v[48:49], v[126:127] op_sel_hi:[1,0]
	v_pk_mul_f32 v[136:137], v[122:123], v[110:111]
	v_pk_mul_f32 v[134:135], v[118:119], v[154:155]
	global_load_dwordx4 v[118:121], v113, s[82:83] offset:64
	v_pk_mul_f32 v[110:111], v[34:35], v[126:127] op_sel_hi:[1,0]
	global_load_dwordx4 v[122:125], v113, s[82:83] offset:80
	v_pk_mul_f32 v[138:139], v[110:111], v[106:107]
	v_pk_mul_f32 v[106:107], v[40:41], v[126:127] op_sel_hi:[1,0]
	v_max3_f32 v42, |v42|, 0, |v43|
	v_pk_mul_f32 v[140:141], v[106:107], v[108:109]
	v_pk_mul_f32 v[106:107], v[36:37], v[126:127] op_sel_hi:[1,0]
	v_pk_mul_f32 v[108:109], v[30:31], v[126:127] op_sel_hi:[1,0]
	v_pk_mul_f32 v[142:143], v[106:107], v[104:105]
	global_load_dwordx4 v[104:107], v113, s[82:83] offset:128
	v_pk_mul_f32 v[144:145], v[108:109], v[102:103]
	v_pk_mul_f32 v[102:103], v[26:27], v[126:127] op_sel_hi:[1,0]
	global_load_dwordx4 v[108:111], v113, s[82:83] offset:144
	v_pk_mul_f32 v[146:147], v[102:103], v[98:99]
	v_pk_mul_f32 v[98:99], v[32:33], v[126:127] op_sel_hi:[1,0]
	v_max3_f32 v42, v42, |v44|, |v45|
	v_pk_mul_f32 v[148:149], v[98:99], v[100:101]
	v_pk_mul_f32 v[98:99], v[28:29], v[126:127] op_sel_hi:[1,0]
	v_pk_mul_f32 v[100:101], v[22:23], v[126:127] op_sel_hi:[1,0]
	v_pk_mul_f32 v[150:151], v[98:99], v[96:97]
	global_load_dwordx4 v[96:99], v113, s[82:83] offset:192
	v_pk_mul_f32 v[152:153], v[100:101], v[94:95]
	v_pk_mul_f32 v[94:95], v[18:19], v[126:127] op_sel_hi:[1,0]
	global_load_dwordx4 v[100:103], v113, s[82:83] offset:208
	v_pk_mul_f32 v[154:155], v[94:95], v[90:91]
	v_pk_mul_f32 v[90:91], v[24:25], v[126:127] op_sel_hi:[1,0]
	v_max3_f32 v42, v42, |v46|, |v47|
	v_pk_mul_f32 v[156:157], v[90:91], v[92:93]
	v_pk_mul_f32 v[90:91], v[20:21], v[126:127] op_sel_hi:[1,0]
	v_pk_mul_f32 v[92:93], v[14:15], v[126:127] op_sel_hi:[1,0]
	v_pk_mul_f32 v[158:159], v[90:91], v[88:89]
	global_load_dwordx4 v[88:91], v113, s[82:83] offset:256
	v_pk_mul_f32 v[160:161], v[92:93], v[86:87]
	v_pk_mul_f32 v[86:87], v[10:11], v[126:127] op_sel_hi:[1,0]
	global_load_dwordx4 v[92:95], v113, s[82:83] offset:272
	v_pk_mul_f32 v[162:163], v[86:87], v[80:81]
	v_pk_mul_f32 v[80:81], v[16:17], v[126:127] op_sel_hi:[1,0]
	v_pk_mul_f32 v[86:87], v[6:7], v[126:127] op_sel_hi:[1,0]
	v_pk_mul_f32 v[164:165], v[80:81], v[82:83]
	v_pk_mul_f32 v[80:81], v[12:13], v[126:127] op_sel_hi:[1,0]
	v_pk_mul_f32 v[166:167], v[86:87], v[84:85]
	v_pk_mul_f32 v[74:75], v[80:81], v[74:75]
	global_load_dwordx4 v[80:83], v113, s[82:83] offset:320
	global_load_dwordx4 v[84:87], v113, s[82:83] offset:336
	v_max3_f32 v42, v42, |v48|, |v49|
	v_max3_f32 v38, v42, |v38|, |v39|
	v_max3_f32 v38, v38, |v40|, |v41|
	v_max3_f32 v34, v38, |v34|, |v35|
	v_max3_f32 v34, v34, |v36|, |v37|
	v_max3_f32 v30, v34, |v30|, |v31|
	v_max3_f32 v30, v30, |v32|, |v33|
	v_max3_f32 v26, v30, |v26|, |v27|
	v_max3_f32 v26, v26, |v28|, |v29|
	v_max3_f32 v22, v26, |v22|, |v23|
	v_max3_f32 v22, v22, |v24|, |v25|
	v_max3_f32 v18, v22, |v18|, |v19|
	v_max3_f32 v18, v18, |v20|, |v21|
	v_max3_f32 v14, v18, |v14|, |v15|
	v_max3_f32 v48, v14, |v16|, |v17|
	v_max3_f32 v10, v48, |v10|, |v11|
	v_max3_f32 v10, v10, |v12|, |v13|
	v_max3_f32 v6, v10, |v6|, |v7|
	v_max3_f32 v6, v6, |v8|, |v9|
	v_pk_mul_f32 v[168:169], v[2:3], v[126:127] op_sel_hi:[1,0]
	v_max3_f32 v2, v6, |v2|, |v3|
	v_max3_f32 v2, v2, |v4|, |v5|
	v_pk_mul_f32 v[76:77], v[168:169], v[76:77]
	s_waitcnt vmcnt(11)
	v_max3_f32 v43, |v50|, 0, |v51|
	v_max3_f32 v43, v43, |v52|, |v53|
	v_pk_mul_f32 v[168:169], v[8:9], v[126:127] op_sel_hi:[1,0]
	v_pk_mul_f32 v[126:127], v[4:5], v[126:127] op_sel_hi:[1,0]
	s_waitcnt vmcnt(10)
	v_max3_f32 v43, v43, |v114|, |v115|
	v_max3_f32 v43, v43, |v116|, |v117|
	v_mul_hi_i32 v14, v54, s39
	ds_bpermute_b32 v4, v235, v2
	v_add_u32_e32 v34, 0x200, v54
	v_add_u32_e32 v26, 0x400, v54
	v_lshlrev_b32_e32 v50, 4, v54
	v_and_b32_e32 v30, 0x70, v50
	s_waitcnt vmcnt(9)
	v_max3_f32 v39, v43, |v118|, |v119|
	v_max3_f32 v39, v39, |v120|, |v121|
	s_waitcnt vmcnt(8)
	v_max3_f32 v35, v39, |v122|, |v123|
	v_max3_f32 v35, v35, |v124|, |v125|
	s_waitcnt lgkmcnt(0)
	v_max_f32_e32 v4, v4, v4
	v_max_f32_e32 v2, v2, v4
	v_mul_f32_e32 v2, 0x41622ae0, v2
	v_mov_b64_e32 v[16:17], s[2:3]
	v_ashrrev_i32_e32 v242, 3, v34
	v_sin_f32_e32 v57, v59
	s_waitcnt vmcnt(7)
	v_max3_f32 v31, v35, |v104|, |v105|
	v_max3_f32 v31, v31, |v106|, |v107|
	v_cos_f32_e32 v58, v58
	s_waitcnt vmcnt(6)
	v_max3_f32 v27, v31, |v108|, |v109|
	v_max3_f32 v27, v27, |v110|, |v111|
	v_mov_b32_e32 v31, v1
	v_lshl_add_u64 v[218:219], s[10:11], 0, v[30:31]
	v_mad_i64_i32 v[30:31], s[0:1], v241, s37, v[218:219]
	v_cos_f32_e32 v59, v59
	v_sin_f32_e32 v61, v63
	s_waitcnt vmcnt(5)
; DI unsigned pack2(float a, float b) { bf2_t v = __builtin_convertvector((f32x2){a, b}, bf2_t); return __builtin_bit_cast(unsigned, v); }
; template <int DQK, int MODE, bool QN, bool KN> ...
;     ...
;         const float x1 = qv[NS - 2][j], x2 = qv[NS - 1][j];
;         qv[NS - 2][j] = x1 * cs - x2 * sn; qv[NS - 1][j] = x2 * cs + x1 * sn;
;       }
;     }
; #pragma unroll
;     for (int s = 0; s < NS; ++s) {
;       u32x4 w; w.x = pack2(qv[s][0], qv[s][1]); w.y = pack2(qv[s][2], qv[s][3]); w.z = pack2(qv[s][4], qv[s][5]); w.w = pack2(qv[s][6], qv[s][7]);
;       qf[s] = __builtin_bit_cast(bf16x8, w);
;     }
;   }
;   f32x4 gk0 = {1.f, 1.f, 1.f, 1.f}, gk1 = {1.f, 1.f, 1.f, 1.f};
;   if (KN) { gk0 = *(const f32x4*)(gk + (tid & 7) * 8); gk1 = *(const f32x4*)(gk + (tid & 7) * 8 + 4); }
;   float sbound = 0.f; bool fixed_shift = false;
;   if (MODE != 2 && QN) {
;     float gqm = 0.f, gkm = 0.f;
; #pragma unroll
;     for (int s = 0; s < NS; ++s)
; #pragma unroll
;       for (int j = 0; j < 8; ++j) { gqm = fmaxf(gqm, fabsf(gq[16 * s + 8 * h + j])); gkm = fmaxf(gkm, fabsf(gk[16 * s + 8 * h + j])); }
;     gqm = fmaxf(gqm, __shfl_xor(gqm, 32)); gkm = fmaxf(gkm, __shfl_xor(gkm, 32));
;     sbound = sqrtf((float)DQK) * 1.4426950408889634f * gqm * gkm * 1.02f + 0.01f;
;     fixed_shift = __builtin_amdgcn_readfirstlane(sbound < 48.f ? 1 : 0) != 0;
;   }
;   f32x16 o[2];
; #pragma unroll
;   for (int a = 0; a < 2; ++a)
; #pragma unroll
;     for (int i = 0; i < 16; ++i) o[a][i] = 0.f;
;   float m_run = -INFINITY, l_run = 0.f, carry = 1.f;
;   u32x4 rk0[NKL], rv0[2], rk1[NKL], rv1[2];
;   const int vtr_off = (4 * h + ((lane & 15) >> 2)) * 64 + (((lane >> 4) & 1) * 16 + 4 * (lane & 3)) * 2;
;     ...
;   const int nsg = nkt >> 1;
;   auto tile_of = [&](int it) { return MODE == 2 ? (nkt - 1 - it) : it; };
;   auto stage_key0 = [&](int sg) { const int sc = sg < nsg ? sg : nsg - 1; return 128 * (MODE == 2 ? (nsg - 1 - sc) : sc); };
;   AT_GLOAD(rk0, rv0, 0)
;   AT_GLOAD(rk1, rv1, 1)
	v_max3_f32 v23, v27, |v96|, |v97|
	v_max3_f32 v23, v23, |v98|, |v99|
	v_cos_f32_e32 v63, v63
	s_waitcnt vmcnt(4)
	v_max3_f32 v19, v23, |v100|, |v101|
	v_max3_f32 v19, v19, |v102|, |v103|
	v_mul_f32_e32 v70, 0.15915494, v68
	v_sin_f32_e32 v65, v67
	v_floor_f32_e32 v70, v70
	v_pk_mul_f32 v[72:73], v[126:127], v[72:73]
	v_pk_mul_f32 v[126:127], v[56:57], v[166:167]
	v_cos_f32_e32 v67, v67
	s_waitcnt vmcnt(3)
	v_max3_f32 v15, v19, |v88|, |v89|
	v_max3_f32 v49, v15, |v90|, |v91|
	v_lshrrev_b32_e32 v15, 31, v14
	s_waitcnt vmcnt(2)
	v_max3_f32 v11, v49, |v92|, |v93|
	v_max3_f32 v11, v11, |v94|, |v95|
	v_ashrrev_i32_e32 v14, 1, v14
	v_add_u32_e32 v238, v14, v15
	v_mad_u64_u32 v[14:15], s[0:1], v238, -12, v[54:55]
	v_lshlrev_b32_e32 v20, 3, v14
	v_ashrrev_i32_e32 v21, 31, v20
	s_waitcnt vmcnt(1)
	v_max3_f32 v7, v11, |v80|, |v81|
	v_max3_f32 v7, v7, |v82|, |v83|
	s_waitcnt vmcnt(0)
	v_max3_f32 v3, v7, |v84|, |v85|
	v_max3_f32 v3, v3, |v86|, |v87|
	ds_bpermute_b32 v5, v235, v3
	v_mul_hi_i32 v15, v34, s39
	v_lshlrev_b64 v[38:39], 1, v[20:21]
	v_lshrrev_b32_e32 v20, 31, v15
	v_ashrrev_i32_e32 v15, 1, v15
	s_waitcnt lgkmcnt(0)
	v_max_f32_e32 v4, v5, v5
	v_add_u32_e32 v239, v15, v20
	v_mul_hi_i32 v15, v26, s39
	v_max_f32_e32 v3, v3, v4
	v_lshrrev_b32_e32 v27, 31, v15
	v_ashrrev_i32_e32 v15, 1, v15
	v_mul_f32_e32 v2, v2, v3
	v_add_u32_e32 v240, v15, v27
	v_fmamk_f32 v6, v2, 0x3f828f5c, v215
	v_mad_u64_u32 v[40:41], s[0:1], v239, -12, v[34:35]
	v_mad_u64_u32 v[44:45], s[0:1], v240, -12, v[26:27]
	v_cmp_gt_f32_e32 vcc, s29, v6
	v_mad_i64_i32 v[18:19], s[0:1], v238, s36, v[16:17]
	v_mad_i64_i32 v[20:21], s[0:1], v239, s36, v[16:17]
	v_lshlrev_b32_e32 v22, 3, v40
	v_mad_i64_i32 v[26:27], s[0:1], v240, s36, v[16:17]
	v_lshlrev_b32_e32 v28, 3, v44
	v_mad_i64_i32 v[34:35], s[0:1], v242, s37, v[218:219]
	v_cndmask_b32_e64 v2, 0, 1, vcc
	v_ashrrev_i32_e32 v23, 31, v22
	v_ashrrev_i32_e32 v29, 31, v28
	v_readfirstlane_b32 s0, v2
	v_add_u32_e32 v2, 0x80, v238
	v_lshlrev_b64 v[42:43], 1, v[22:23]
	v_lshlrev_b64 v[46:47], 1, v[28:29]
	s_bitcmp1_b32 s0, 0
	v_mad_i64_i32 v[2:3], s[0:1], v2, s36, v[16:17]
	v_lshl_add_u64 v[18:19], v[18:19], 0, v[38:39]
	v_lshl_add_u64 v[22:23], v[20:21], 0, v[42:43]
	v_lshl_add_u64 v[26:27], v[26:27], 0, v[46:47]
	v_lshl_add_u64 v[2:3], v[2:3], 0, v[38:39]
	global_load_dwordx4 v[18:21], v[18:19], off
	s_nop 0
	global_load_dwordx4 v[22:25], v[22:23], off
	v_add_u32_e32 v4, 0x80, v240
	global_load_dwordx4 v[26:29], v[26:27], off
	v_mad_i64_i32 v[4:5], s[0:1], v4, s36, v[16:17]
	global_load_dwordx4 v[184:187], v[2:3], off
	v_add_u32_e32 v2, 0x80, v239
	v_mad_i64_i32 v[2:3], s[0:1], v2, s36, v[16:17]
	global_load_dwordx4 v[30:33], v[30:31], off
	v_lshl_add_u64 v[2:3], v[2:3], 0, v[42:43]
	global_load_dwordx4 v[34:37], v[34:35], off
	v_lshl_add_u64 v[4:5], v[4:5], 0, v[46:47]
	global_load_dwordx4 v[188:191], v[2:3], off
	global_load_dwordx4 v[192:195], v[4:5], off
	v_add_u32_e32 v2, 0x80, v241
	v_mad_i64_i32 v[2:3], s[0:1], v2, s37, v[218:219]
	v_add_u32_e32 v4, 0x80, v242
	v_mad_i64_i32 v[4:5], s[0:1], v4, s37, v[218:219]
	global_load_dwordx4 v[196:199], v[2:3], off
	global_load_dwordx4 v[200:203], v[4:5], off
	v_mul_lo_u32 v2, v238, s40
	v_add_u32_e32 v2, 0x110, v2
	v_lshlrev_b32_e32 v3, 4, v14
	v_add_u32_e32 v244, v2, v3
	v_mul_lo_u32 v2, v239, s40
	v_add_u32_e32 v2, 0x110, v2
	v_lshlrev_b32_e32 v3, 4, v40
	v_fma_f32 v70, v68, 0.15915494, -v70
	v_pk_mul_f32 v[78:79], v[168:169], v[78:79]
	v_pk_fma_f32 v[126:127], v[58:59], v[160:161], v[126:127] neg_lo:[0,0,1] neg_hi:[0,0,1]
	v_pk_mul_f32 v[58:59], v[58:59], v[166:167]
	v_add_u32_e32 v245, v2, v3
	v_mul_lo_u32 v2, v240, s40
	v_sin_f32_e32 v68, v70
	v_pk_fma_f32 v[56:57], v[56:57], v[160:161], v[58:59]
	v_pk_mul_f32 v[58:59], v[60:61], v[78:79]
	v_add_u32_e32 v2, 0x110, v2
	v_lshlrev_b32_e32 v3, 4, v44
	v_cos_f32_e32 v70, v70
	v_pk_fma_f32 v[58:59], v[62:63], v[164:165], v[58:59] neg_lo:[0,0,1] neg_hi:[0,0,1]
	v_pk_mul_f32 v[62:63], v[62:63], v[78:79]
	v_add_u32_e32 v246, v2, v3
	v_lshlrev_b32_e32 v2, 11, v54
	v_pk_fma_f32 v[60:61], v[60:61], v[164:165], v[62:63]
	v_pk_mul_f32 v[62:63], v[64:65], v[76:77]
	v_lshlrev_b32_e32 v7, 3, v54
	s_cselect_b64 s[0:1], -1, 0
	v_and_b32_e32 v2, 0x2000, v2
	v_and_b32_e32 v3, 48, v50
	v_pk_fma_f32 v[62:63], v[66:67], v[162:163], v[62:63] neg_lo:[0,0,1] neg_hi:[0,0,1]
	v_pk_mul_f32 v[66:67], v[66:67], v[76:77]
	v_cndmask_b32_e64 v16, 0, -v6, s[0:1]
	v_add3_u32 v4, s34, v2, v3
	v_and_b32_e32 v40, 0xffffffc0, v7
	v_lshlrev_b32_e32 v6, 2, v54
	v_and_b32_e32 v7, 16, v54
	v_pk_fma_f32 v[64:65], v[64:65], v[162:163], v[66:67]
	v_pk_mul_f32 v[66:67], v[68:69], v[72:73]
	v_add_u32_e32 v248, v4, v40
	v_and_or_b32 v6, v6, 12, v7
	v_pk_fma_f32 v[66:67], v[70:71], v[74:75], v[66:67] neg_lo:[0,0,1] neg_hi:[0,0,1]
	v_pk_mul_f32 v[70:71], v[70:71], v[72:73]
	v_lshlrev_b32_e32 v4, 8, v112
	v_and_b32_e32 v5, 0xc0, v50
	v_lshlrev_b32_e32 v6, 1, v6
	v_mov_b32_e32 v14, v1
	v_mov_b32_e32 v15, v1
	v_pk_fma_f32 v[68:69], v[68:69], v[74:75], v[70:71]
	v_cvt_pk_bf16_f32 v177, v58, v59
	v_cvt_pk_bf16_f32 v178, v62, v63
	v_cvt_pk_bf16_f32 v180, v56, v57
	v_cvt_pk_bf16_f32 v181, v60, v61
	v_or3_b32 v249, v4, v5, v6
	v_lshl_add_u64 v[220:221], s[2:3], 0, v[38:39]
	v_lshl_add_u64 v[222:223], s[2:3], 0, v[42:43]
	v_lshl_add_u64 v[224:225], s[2:3], 0, v[46:47]
	v_mov_b32_e32 v4, v1
	v_mov_b32_e32 v5, v1
	s_waitcnt vmcnt(9)
; template <int DQK, int MODE, bool QN, bool KN> ...
;     ...
;   f32x16 o[2];
; #pragma unroll
;   for (int a = 0; a < 2; ++a)
; #pragma unroll
;     for (int i = 0; i < 16; ++i) o[a][i] = 0.f;
;   float m_run = -INFINITY, l_run = 0.f, carry = 1.f;
;   u32x4 rk0[NKL], rv0[2], rk1[NKL], rv1[2];
;   const int vtr_off = (4 * h + ((lane & 15) >> 2)) * 64 + (((lane >> 4) & 1) * 16 + 4 * (lane & 3)) * 2;
;     ...
;   const int nsg = nkt >> 1;
;   auto tile_of = [&](int it) { return MODE == 2 ? (nkt - 1 - it) : it; };
;   auto stage_key0 = [&](int sg) { const int sc = sg < nsg ? sg : nsg - 1; return 128 * (MODE == 2 ? (nsg - 1 - sc) : sc); };
;   AT_GLOAD(rk0, rv0, 0)
;   AT_GLOAD(rk1, rv1, 1)
;   AT_SWRITE(rk0, rv0, 0)
;   __syncthreads();
	ds_write_b128 v244, v[18:21]
	s_waitcnt vmcnt(8)
	ds_write_b128 v245, v[22:25]
	v_mov_b32_e32 v6, v1
	s_waitcnt vmcnt(7)
	ds_write_b128 v246, v[26:29]
	s_waitcnt vmcnt(5)
	ds_write_b128 v248, v[30:33] offset:26624
	s_waitcnt vmcnt(4)
	ds_write_b128 v248, v[34:37] offset:30720
	v_add_u32_e32 v32, 0x110, v0
	v_mul_u32_u24_e32 v33, 0xd0, v55
	v_add3_u32 v34, s41, v2, v3
	v_mov_b32_e32 v0, v1
	v_mov_b32_e32 v2, v1
	v_mov_b32_e32 v3, v1
	v_mov_b32_e32 v7, v1
	v_mov_b32_e32 v8, v1
	v_mov_b32_e32 v9, v1
	v_mov_b32_e32 v10, v1
	v_mov_b32_e32 v11, v1
	v_mov_b32_e32 v12, v1
	v_mov_b32_e32 v13, v1
	v_add_u32_e32 v250, v34, v40
	v_add_u32_e32 v251, v32, v33
	v_mov_b64_e32 v[46:47], v[14:15]
	v_mov_b64_e32 v[62:63], v[14:15]
	v_cvt_pk_bf16_f32 v160, v128, v129
	v_cvt_pk_bf16_f32 v161, v132, v133
	v_cvt_pk_bf16_f32 v162, v130, v131
	v_cvt_pk_bf16_f32 v163, v134, v135
	v_cvt_pk_bf16_f32 v164, v136, v137
	v_cvt_pk_bf16_f32 v165, v140, v141
	v_cvt_pk_bf16_f32 v166, v138, v139
	v_cvt_pk_bf16_f32 v167, v142, v143
	v_cvt_pk_bf16_f32 v168, v144, v145
	v_cvt_pk_bf16_f32 v169, v148, v149
	v_cvt_pk_bf16_f32 v170, v146, v147
	v_cvt_pk_bf16_f32 v171, v150, v151
	v_cvt_pk_bf16_f32 v172, v152, v153
	v_cvt_pk_bf16_f32 v173, v156, v157
	v_cvt_pk_bf16_f32 v174, v154, v155
	v_cvt_pk_bf16_f32 v175, v158, v159
	v_cvt_pk_bf16_f32 v176, v126, v127
	v_cvt_pk_bf16_f32 v179, v66, v67
	v_cvt_pk_bf16_f32 v182, v64, v65
	v_cvt_pk_bf16_f32 v183, v68, v69
	s_xor_b64 s[0:1], s[0:1], -1
	v_mov_b32_e32 v17, v16
	v_mov_b32_e32 v18, v16
	v_mov_b32_e32 v19, v16
	v_mov_b32_e32 v20, v16
	v_mov_b32_e32 v21, v16
	v_mov_b32_e32 v22, v16
	v_mov_b32_e32 v23, v16
	v_mov_b32_e32 v24, v16
	v_mov_b32_e32 v25, v16
	v_mov_b32_e32 v26, v16
	v_mov_b32_e32 v27, v16
	v_mov_b32_e32 v28, v16
	v_mov_b32_e32 v29, v16
	v_mov_b32_e32 v30, v16
	v_mov_b32_e32 v31, v16
	v_mov_b64_e32 v[44:45], v[12:13]
	v_mov_b64_e32 v[42:43], v[10:11]
	v_mov_b64_e32 v[40:41], v[8:9]
	v_mov_b64_e32 v[38:39], v[6:7]
	v_mov_b64_e32 v[36:37], v[4:5]
	v_mov_b64_e32 v[34:35], v[2:3]
	v_mov_b64_e32 v[32:33], v[0:1]
	v_mov_b64_e32 v[60:61], v[12:13]
	v_mov_b64_e32 v[58:59], v[10:11]
	v_mov_b64_e32 v[56:57], v[8:9]
	v_mov_b64_e32 v[54:55], v[6:7]
	v_mov_b64_e32 v[52:53], v[4:5]
	v_mov_b64_e32 v[50:51], v[2:3]
	v_mov_b64_e32 v[48:49], v[0:1]
	v_mov_b64_e32 v[128:129], v[32:33]
	v_mov_b64_e32 v[130:131], v[34:35]
	v_mov_b64_e32 v[132:133], v[36:37]
	v_mov_b64_e32 v[134:135], v[38:39]
	v_mov_b64_e32 v[136:137], v[40:41]
	v_mov_b64_e32 v[138:139], v[42:43]
	v_mov_b64_e32 v[140:141], v[44:45]
	v_mov_b64_e32 v[142:143], v[46:47]
	v_mov_b64_e32 v[96:97], v[48:49]
	v_mov_b64_e32 v[98:99], v[50:51]
	v_mov_b64_e32 v[100:101], v[52:53]
	v_mov_b64_e32 v[102:103], v[54:55]
	v_mov_b64_e32 v[104:105], v[56:57]
	v_mov_b64_e32 v[106:107], v[58:59]
	v_mov_b64_e32 v[108:109], v[60:61]
	v_mov_b64_e32 v[110:111], v[62:63]
	s_waitcnt lgkmcnt(0)
	s_barrier
	s_branch .LBB0_1198
